# G2 and F3 epilogues: bf16 copy rows stored nt as well
# baseline (speedup 1.0000x reference)
; #define NTL(p) __builtin_nontemporal_load((const f32x4*)(p))
; #define NTS(v, p) __builtin_nontemporal_store((v), (f32x4*)(p))
; __device__ __forceinline__ unsigned cvt_pk_bf16(float lo, float hi) { unsigned r; asm volatile("v_cvt_pk_bf16_f32 %0, %1, %2" : "=v"(r) : "v"(lo), "v"(hi)); return r; }
;     __device__ __forceinline__ void operator()(AccT& acc, const Unit& u, int wr, int wc, int fr, int fq) const {
;     ...
;         const int row0 = u.pm * 256 + wr * 64 + fr, col0 = u.pn * 256 + wc * 32 + 8 * fq;
;         f32x4 xv[2][4];
;         { const int row = row0; const float* xr = (row < HALF_TOK ? x0 + (size_t)row * DM : x1 + (size_t)(row - HALF_TOK) * DM) + col0;
;           xv[0][0] = NTL(xr); xv[0][1] = NTL(xr + 4); xv[0][2] = NTL(xr + 128); xv[0][3] = NTL(xr + 132); }
; #pragma unroll
;         for (int r = 0; r < 8; ++r) { const int ai = r >> 2, m = r & 3; const int row = row0 + ai * 128 + m * 16;
;             if (r < 7) { const int rn = row0 + ((r + 1) >> 2) * 128 + ((r + 1) & 3) * 16; const float* xr = (rn < HALF_TOK ? x0 + (size_t)rn * DM : x1 + (size_t)(rn - HALF_TOK) * DM) + col0;
;                 xv[(r + 1) & 1][0] = NTL(xr); xv[(r + 1) & 1][1] = NTL(xr + 4); xv[(r + 1) & 1][2] = NTL(xr + 128); xv[(r + 1) & 1][3] = NTL(xr + 132); }
;             float* hr = H + (size_t)row * DM + col0; float ss = 0.f;
; #pragma unroll
;             for (int bj = 0; bj < 2; ++bj) {
;                 f32x4 v0 = acc[ai][bj][m][0] + xv[r & 1][2 * bj], v1 = acc[ai][bj][m][1] + xv[r & 1][2 * bj + 1];
;                 NTS(v0, hr + bj * 128); NTS(v1, hr + bj * 128 + 4);
;                 u32x4 w; w.x = cvt_pk_bf16(v0[0], v0[1]); w.y = cvt_pk_bf16(v0[2], v0[3]); w.z = cvt_pk_bf16(v1[0], v1[1]); w.w = cvt_pk_bf16(v1[2], v1[3]);
;                 *(u32x4*)(HB + (size_t)row * DM + col0 + bj * 128) = w;
; #pragma unroll
;                 for (int j = 0; j < 4; ++j) ss += v0[j] * v0[j] + v1[j] * v1[j]; }
;             ss += __shfl_xor(ss, 16); ss += __shfl_xor(ss, 32);
;             if (fq == 0) unsafeAtomicAdd(rss + row, ss); __builtin_amdgcn_sched_barrier(0); }
.LBB0_48:
	s_lshl_b32 s16, s76, 8
	v_mov_b32_e32 v130, v164
	s_add_i32 s16, s16, s50
	v_mov_b32_e32 v134, v165
	v_add_u32_e32 v158, s16, v130
	s_lshl_b32 s16, s77, 8
	s_or_b32 s16, s16, s51
	v_readlane_b32 s60, v254, 34
	v_lshl_add_u32 v156, v134, 3, s16
	s_movk_i32 s16, 0x4000
	v_cmp_gt_i32_e32 vcc, s16, v158
	v_add_u32_e32 v130, 0xffffc000, v158
	v_ashrrev_i32_e32 v159, 31, v158
	v_readlane_b32 s61, v254, 35
	v_readlane_b32 s62, v254, 36
	v_readlane_b32 s63, v254, 37
	v_cndmask_b32_e32 v131, 0, v159, vcc
	v_cndmask_b32_e32 v130, v130, v158, vcc
	v_mov_b32_e32 v135, s63
	v_mov_b32_e32 v136, s61
	v_mov_b32_e32 v137, s62
	v_mov_b32_e32 v138, s60
	v_cndmask_b32_e32 v133, v135, v136, vcc
	v_cndmask_b32_e32 v132, v137, v138, vcc
	v_lshlrev_b64 v[130:131], 12, v[130:131]
	v_ashrrev_i32_e32 v157, 31, v156
	v_lshl_add_u64 v[130:131], v[132:133], 0, v[130:131]
	v_lshlrev_b64 v[160:161], 2, v[156:157]
	v_lshl_add_u64 v[130:131], v[130:131], 0, v[160:161]
	global_load_dwordx4 v[170:173], v[130:131], off offset:16 nt
	global_load_dwordx4 v[176:179], v[130:131], off nt
	global_load_dwordx4 v[180:183], v[130:131], off offset:528 nt
	global_load_dwordx4 v[188:191], v[130:131], off offset:512 nt
	v_add_u32_e32 v174, 16, v158
	v_cmp_gt_i32_e64 s[42:43], s79, v158
	v_add_u32_e32 v130, 0xffffc010, v158
	v_ashrrev_i32_e32 v175, 31, v174
	v_cndmask_b32_e64 v131, 0, v175, s[42:43]
	v_cndmask_b32_e64 v130, v130, v174, s[42:43]
	v_cndmask_b32_e64 v133, v135, v136, s[42:43]
	v_cndmask_b32_e64 v132, v137, v138, s[42:43]
	v_lshlrev_b64 v[130:131], 12, v[130:131]
	v_lshl_add_u64 v[130:131], v[132:133], 0, v[130:131]
	v_cmp_eq_u32_e32 vcc, 0, v134
	v_lshl_add_u64 v[134:135], v[130:131], 0, v[160:161]
	global_load_dwordx4 v[138:141], v[134:135], off offset:16 nt
	global_load_dwordx4 v[142:145], v[134:135], off nt
	global_load_dwordx4 v[130:133], v[134:135], off offset:528 nt
	s_nop 0
	global_load_dwordx4 v[134:137], v[134:135], off offset:512 nt
	v_lshlrev_b64 v[184:185], 12, v[158:159]
	v_lshl_add_u64 v[184:185], s[22:23], 0, v[184:185]
	v_lshl_add_u64 v[184:185], v[184:185], 0, v[160:161]
	v_readlane_b32 s64, v254, 38
	v_readlane_b32 s65, v254, 39
	v_readlane_b32 s66, v254, 40
	v_readlane_b32 s67, v254, 41
	v_readlane_b32 s68, v254, 42
	v_readlane_b32 s69, v254, 43
	v_readlane_b32 s70, v254, 44
	v_readlane_b32 s71, v254, 45
	v_readlane_b32 s72, v254, 46
	v_readlane_b32 s73, v254, 47
	v_readlane_b32 s74, v254, 48
	v_readlane_b32 s75, v254, 49
	s_waitcnt vmcnt(0)
	v_pk_add_f32 v[126:127], v[126:127], v[170:171]
	v_pk_add_f32 v[124:125], v[124:125], v[178:179]
	v_pk_add_f32 v[122:123], v[122:123], v[176:177]
	v_pk_add_f32 v[128:129], v[128:129], v[172:173]
	global_store_dwordx4 v[184:185], v[122:125], off nt
	global_store_dwordx4 v[184:185], v[126:129], off offset:16 nt
	v_cvt_pk_bf16_f32 v170, v122, v123
	v_cvt_pk_bf16_f32 v171, v124, v125
	v_cvt_pk_bf16_f32 v172, v126, v127
	v_lshlrev_b64 v[176:177], 11, v[158:159]
	v_lshl_add_u64 v[176:177], s[6:7], 0, v[176:177]
	v_mul_f32_e32 v126, v126, v126
	v_fmac_f32_e32 v126, v122, v122
	v_mul_f32_e32 v122, v127, v127
	v_fmac_f32_e32 v122, v123, v123
	v_mul_f32_e32 v123, v128, v128
	v_add_f32_e32 v122, v126, v122
	v_fmac_f32_e32 v123, v124, v124
	v_add_f32_e32 v122, v123, v122
	v_mul_f32_e32 v123, v129, v129
	v_lshl_add_u64 v[176:177], v[156:157], 1, v[176:177]
	v_fmac_f32_e32 v123, v125, v125
	v_pk_add_f32 v[120:121], v[120:121], v[190:191]
	v_pk_add_f32 v[118:119], v[118:119], v[188:189]
	v_pk_add_f32 v[114:115], v[114:115], v[180:181]
	v_cvt_pk_bf16_f32 v173, v128, v129
	global_store_dwordx4 v[176:177], v[170:173], off nt
	v_add_f32_e32 v126, v123, v122
	v_pk_add_f32 v[116:117], v[116:117], v[182:183]
	global_store_dwordx4 v[184:185], v[118:121], off offset:512 nt
	global_store_dwordx4 v[184:185], v[114:117], off offset:528 nt
	v_cvt_pk_bf16_f32 v122, v118, v119
	v_cvt_pk_bf16_f32 v123, v120, v121
	v_cvt_pk_bf16_f32 v124, v114, v115
	v_cvt_pk_bf16_f32 v125, v116, v117
	global_store_dwordx4 v[176:177], v[122:125], off offset:256 nt
	s_nop 0
	v_mul_f32_e32 v114, v114, v114
	v_fmac_f32_e32 v114, v118, v118
	v_mul_f32_e32 v115, v115, v115
	v_add_f32_e32 v114, v114, v126
	v_fmac_f32_e32 v115, v119, v119
	v_add_f32_e32 v114, v115, v114
	v_mul_f32_e32 v115, v116, v116
	v_fmac_f32_e32 v115, v120, v120
	v_add_f32_e32 v114, v115, v114
	v_mul_f32_e32 v115, v117, v117
	v_fmac_f32_e32 v115, v121, v121
	v_and_b32_e32 v116, 64, v203
	v_add_f32_e32 v114, v115, v114
	v_xor_b32_e32 v115, 16, v203
	v_add_u32_e32 v116, 64, v116
	v_cmp_lt_i32_e64 s[42:43], v115, v116
	s_nop 1
	v_cndmask_b32_e64 v115, v203, v115, s[42:43]
	v_lshlrev_b32_e32 v169, 2, v115
	ds_bpermute_b32 v115, v169, v114
	s_waitcnt lgkmcnt(0)
	v_add_f32_e32 v114, v114, v115
	v_xor_b32_e32 v115, 32, v203
	v_cmp_lt_i32_e64 s[42:43], v115, v116
	s_nop 1
	v_cndmask_b32_e64 v115, v203, v115, s[42:43]
	v_lshlrev_b32_e32 v170, 2, v115
	ds_bpermute_b32 v115, v170, v114
	s_and_saveexec_b64 s[16:17], vcc
	s_cbranch_execz .LBB0_50
	v_lshl_add_u64 v[116:117], v[158:159], 2, s[8:9]
	s_waitcnt lgkmcnt(0)
	v_add_f32_e32 v114, v114, v115
	global_atomic_add_f32 v[116:117], v114, off
; #define NTL(p) __builtin_nontemporal_load((const f32x4*)(p))
; #define NTS(v, p) __builtin_nontemporal_store((v), (f32x4*)(p))
; __device__ __forceinline__ unsigned cvt_pk_bf16(float lo, float hi) { unsigned r; asm volatile("v_cvt_pk_bf16_f32 %0, %1, %2" : "=v"(r) : "v"(lo), "v"(hi)); return r; }
;     __device__ __forceinline__ void operator()(AccT& acc, const Unit& u, int wr, int wc, int fr, int fq) const {
;     ...
;         for (int r = 0; r < 8; ++r) { const int ai = r >> 2, m = r & 3; const int row = row0 + ai * 128 + m * 16;
;             if (r < 7) { const int rn = row0 + ((r + 1) >> 2) * 128 + ((r + 1) & 3) * 16; const float* xr = (rn < HALF_TOK ? x0 + (size_t)rn * DM : x1 + (size_t)(rn - HALF_TOK) * DM) + col0;
;                 xv[(r + 1) & 1][0] = NTL(xr); xv[(r + 1) & 1][1] = NTL(xr + 4); xv[(r + 1) & 1][2] = NTL(xr + 128); xv[(r + 1) & 1][3] = NTL(xr + 132); }
;             float* hr = H + (size_t)row * DM + col0; float ss = 0.f;
; #pragma unroll
;             for (int bj = 0; bj < 2; ++bj) {
;                 f32x4 v0 = acc[ai][bj][m][0] + xv[r & 1][2 * bj], v1 = acc[ai][bj][m][1] + xv[r & 1][2 * bj + 1];
;                 NTS(v0, hr + bj * 128); NTS(v1, hr + bj * 128 + 4);
;                 u32x4 w; w.x = cvt_pk_bf16(v0[0], v0[1]); w.y = cvt_pk_bf16(v0[2], v0[3]); w.z = cvt_pk_bf16(v1[0], v1[1]); w.w = cvt_pk_bf16(v1[2], v1[3]);
;                 *(u32x4*)(HB + (size_t)row * DM + col0 + bj * 128) = w;
; #pragma unroll
;                 for (int j = 0; j < 4; ++j) ss += v0[j] * v0[j] + v1[j] * v1[j]; }
;             ss += __shfl_xor(ss, 16); ss += __shfl_xor(ss, 32);
;             if (fq == 0) unsafeAtomicAdd(rss + row, ss); __builtin_amdgcn_sched_barrier(0); }
.LBB0_50:
	s_or_b64 exec, exec, s[16:17]
	v_readlane_b32 s60, v254, 34
	v_add_u32_e32 v176, 32, v158
	v_readlane_b32 s61, v254, 35
	v_readlane_b32 s63, v254, 37
	v_ashrrev_i32_e32 v177, 31, v176
	v_add_u32_e32 v114, 0xffffc020, v158
	v_cmp_gt_i32_e64 s[42:43], s83, v158
	v_readlane_b32 s62, v254, 36
	v_mov_b32_e32 v116, s63
	v_mov_b32_e32 v117, s61
	s_waitcnt lgkmcnt(0)
	v_cndmask_b32_e64 v115, 0, v177, s[42:43]
	v_cndmask_b32_e64 v114, v114, v176, s[42:43]
	v_cndmask_b32_e64 v117, v116, v117, s[42:43]
	v_mov_b32_e32 v116, s62
	v_mov_b32_e32 v118, s60
	v_cndmask_b32_e64 v116, v116, v118, s[42:43]
	v_lshlrev_b64 v[114:115], 12, v[114:115]
	v_lshl_add_u64 v[114:115], v[116:117], 0, v[114:115]
	v_lshl_add_u64 v[118:119], v[114:115], 0, v[160:161]
	global_load_dwordx4 v[122:125], v[118:119], off offset:16 nt
	global_load_dwordx4 v[126:129], v[118:119], off nt
	global_load_dwordx4 v[114:117], v[118:119], off offset:528 nt
	s_nop 0
	global_load_dwordx4 v[118:121], v[118:119], off offset:512 nt
	v_lshlrev_b64 v[172:173], 12, v[174:175]
	v_lshl_add_u64 v[172:173], s[22:23], 0, v[172:173]
	v_lshl_add_u64 v[172:173], v[172:173], 0, v[160:161]
	v_pk_add_f32 v[112:113], v[112:113], v[144:145]
	v_pk_add_f32 v[110:111], v[110:111], v[142:143]
	v_pk_add_f32 v[106:107], v[106:107], v[138:139]
	v_pk_add_f32 v[108:109], v[108:109], v[140:141]
	global_store_dwordx4 v[172:173], v[110:113], off nt
	global_store_dwordx4 v[172:173], v[106:109], off offset:16 nt
	v_cvt_pk_bf16_f32 v138, v110, v111
	v_cvt_pk_bf16_f32 v139, v112, v113
	v_cvt_pk_bf16_f32 v140, v106, v107
	v_pk_add_f32 v[102:103], v[102:103], v[134:135]
	v_cvt_pk_bf16_f32 v141, v108, v109
	s_nop 0
	v_mul_f32_e32 v106, v106, v106
	v_mul_f32_e32 v107, v107, v107
	v_fmac_f32_e32 v106, v110, v110
	v_fmac_f32_e32 v107, v111, v111
	v_add_f32_e32 v106, v106, v107
	v_mul_f32_e32 v107, v108, v108
	v_fmac_f32_e32 v107, v112, v112
	v_add_f32_e32 v106, v107, v106
	v_mul_f32_e32 v107, v109, v109
	v_fmac_f32_e32 v107, v113, v113
	v_add_f32_e32 v110, v107, v106
	v_pk_add_f32 v[106:107], v[98:99], v[130:131]
	v_pk_add_f32 v[108:109], v[100:101], v[132:133]
	v_mul_f32_e32 v98, v106, v106
	v_fmac_f32_e32 v98, v102, v102
	v_mul_f32_e32 v99, v107, v107
	v_add_f32_e32 v98, v98, v110
	v_fmac_f32_e32 v99, v103, v103
	v_pk_add_f32 v[104:105], v[104:105], v[136:137]
	v_add_f32_e32 v98, v99, v98
	v_mul_f32_e32 v99, v108, v108
	v_fmac_f32_e32 v99, v104, v104
	v_add_f32_e32 v98, v99, v98
	v_mul_f32_e32 v99, v109, v109
	v_fmac_f32_e32 v99, v105, v105
	v_add_f32_e32 v98, v99, v98
	ds_bpermute_b32 v99, v169, v98
	v_lshlrev_b64 v[142:143], 11, v[174:175]
	v_lshl_add_u64 v[142:143], s[6:7], 0, v[142:143]
	v_lshl_add_u64 v[142:143], v[156:157], 1, v[142:143]
	v_readlane_b32 s64, v254, 38
	s_waitcnt lgkmcnt(0)
	v_add_f32_e32 v98, v98, v99
	ds_bpermute_b32 v99, v170, v98
	v_readlane_b32 s65, v254, 39
	v_readlane_b32 s66, v254, 40
	v_readlane_b32 s67, v254, 41
	v_readlane_b32 s68, v254, 42
	v_readlane_b32 s69, v254, 43
	v_readlane_b32 s70, v254, 44
	v_readlane_b32 s71, v254, 45
	v_readlane_b32 s72, v254, 46
	v_readlane_b32 s73, v254, 47
	v_readlane_b32 s74, v254, 48
	v_readlane_b32 s75, v254, 49
	global_store_dwordx4 v[142:143], v[138:141], off nt
	global_store_dwordx4 v[172:173], v[102:105], off offset:512 nt
	global_store_dwordx4 v[172:173], v[106:109], off offset:528 nt
	v_cvt_pk_bf16_f32 v100, v102, v103
	v_cvt_pk_bf16_f32 v101, v104, v105
	s_nop 0
	v_cvt_pk_bf16_f32 v102, v106, v107
	v_cvt_pk_bf16_f32 v103, v108, v109
	global_store_dwordx4 v[142:143], v[100:103], off offset:256 nt
	s_and_saveexec_b64 s[16:17], vcc
	s_cbranch_execz .LBB0_52
	v_lshl_add_u64 v[100:101], v[174:175], 2, s[8:9]
	s_waitcnt lgkmcnt(0)
	v_add_f32_e32 v98, v98, v99
	global_atomic_add_f32 v[100:101], v98, off
.LBB0_52:
	s_or_b64 exec, exec, s[16:17]
	v_readlane_b32 s60, v254, 34
	v_add_u32_e32 v130, 48, v158
	v_readlane_b32 s61, v254, 35
	v_readlane_b32 s63, v254, 37
	v_ashrrev_i32_e32 v131, 31, v130
	v_add_u32_e32 v98, 0xffffc030, v158
	v_cmp_gt_i32_e64 s[42:43], s84, v158
	v_readlane_b32 s62, v254, 36
	v_mov_b32_e32 v100, s63
	v_mov_b32_e32 v101, s61
	s_waitcnt lgkmcnt(0)
	v_cndmask_b32_e64 v99, 0, v131, s[42:43]
	v_cndmask_b32_e64 v98, v98, v130, s[42:43]
	v_cndmask_b32_e64 v101, v100, v101, s[42:43]
	v_mov_b32_e32 v100, s62
	v_mov_b32_e32 v102, s60
	v_cndmask_b32_e64 v100, v100, v102, s[42:43]
	v_lshlrev_b64 v[98:99], 12, v[98:99]
	v_lshl_add_u64 v[98:99], v[100:101], 0, v[98:99]
	v_lshl_add_u64 v[102:103], v[98:99], 0, v[160:161]
	global_load_dwordx4 v[106:109], v[102:103], off offset:16 nt
	global_load_dwordx4 v[110:113], v[102:103], off nt
	global_load_dwordx4 v[98:101], v[102:103], off offset:528 nt
	s_nop 0
	global_load_dwordx4 v[102:105], v[102:103], off offset:512 nt
	v_lshlrev_b64 v[132:133], 12, v[176:177]
	v_lshl_add_u64 v[132:133], s[22:23], 0, v[132:133]
	v_lshl_add_u64 v[132:133], v[132:133], 0, v[160:161]
	s_waitcnt vmcnt(12)
	v_pk_add_f32 v[96:97], v[96:97], v[128:129]
	v_pk_add_f32 v[94:95], v[94:95], v[126:127]
	v_pk_add_f32 v[90:91], v[90:91], v[122:123]
	v_pk_add_f32 v[92:93], v[92:93], v[124:125]
	global_store_dwordx4 v[132:133], v[94:97], off nt
	global_store_dwordx4 v[132:133], v[90:93], off offset:16 nt
	v_cvt_pk_bf16_f32 v122, v94, v95
	v_cvt_pk_bf16_f32 v123, v96, v97
	v_cvt_pk_bf16_f32 v124, v90, v91
	s_waitcnt vmcnt(12)
; #define NTL(p) __builtin_nontemporal_load((const f32x4*)(p))
; #define NTS(v, p) __builtin_nontemporal_store((v), (f32x4*)(p))
; __device__ __forceinline__ unsigned cvt_pk_bf16(float lo, float hi) { unsigned r; asm volatile("v_cvt_pk_bf16_f32 %0, %1, %2" : "=v"(r) : "v"(lo), "v"(hi)); return r; }
;     __device__ __forceinline__ void operator()(AccT& acc, const Unit& u, int wr, int wc, int fr, int fq) const {
;     ...
;         for (int r = 0; r < 8; ++r) { const int ai = r >> 2, m = r & 3; const int row = row0 + ai * 128 + m * 16;
;             if (r < 7) { const int rn = row0 + ((r + 1) >> 2) * 128 + ((r + 1) & 3) * 16; const float* xr = (rn < HALF_TOK ? x0 + (size_t)rn * DM : x1 + (size_t)(rn - HALF_TOK) * DM) + col0;
;                 xv[(r + 1) & 1][0] = NTL(xr); xv[(r + 1) & 1][1] = NTL(xr + 4); xv[(r + 1) & 1][2] = NTL(xr + 128); xv[(r + 1) & 1][3] = NTL(xr + 132); }
;             float* hr = H + (size_t)row * DM + col0; float ss = 0.f;
; #pragma unroll
;             for (int bj = 0; bj < 2; ++bj) {
;                 f32x4 v0 = acc[ai][bj][m][0] + xv[r & 1][2 * bj], v1 = acc[ai][bj][m][1] + xv[r & 1][2 * bj + 1];
;                 NTS(v0, hr + bj * 128); NTS(v1, hr + bj * 128 + 4);
;                 u32x4 w; w.x = cvt_pk_bf16(v0[0], v0[1]); w.y = cvt_pk_bf16(v0[2], v0[3]); w.z = cvt_pk_bf16(v1[0], v1[1]); w.w = cvt_pk_bf16(v1[2], v1[3]);
;                 *(u32x4*)(HB + (size_t)row * DM + col0 + bj * 128) = w;
; #pragma unroll
;                 for (int j = 0; j < 4; ++j) ss += v0[j] * v0[j] + v1[j] * v1[j]; }
;             ss += __shfl_xor(ss, 16); ss += __shfl_xor(ss, 32);
;             if (fq == 0) unsafeAtomicAdd(rss + row, ss); __builtin_amdgcn_sched_barrier(0); }
	v_pk_add_f32 v[86:87], v[86:87], v[118:119]
	v_cvt_pk_bf16_f32 v125, v92, v93
	v_mul_f32_e32 v90, v90, v90
	v_mul_f32_e32 v91, v91, v91
	v_fmac_f32_e32 v90, v94, v94
	v_fmac_f32_e32 v91, v95, v95
	v_add_f32_e32 v90, v90, v91
	v_mul_f32_e32 v91, v92, v92
	v_fmac_f32_e32 v91, v96, v96
	v_add_f32_e32 v90, v91, v90
	v_mul_f32_e32 v91, v93, v93
	v_fmac_f32_e32 v91, v97, v97
	v_add_f32_e32 v94, v91, v90
	v_pk_add_f32 v[90:91], v[82:83], v[114:115]
	v_pk_add_f32 v[92:93], v[84:85], v[116:117]
	v_mul_f32_e32 v82, v90, v90
	v_fmac_f32_e32 v82, v86, v86
	v_mul_f32_e32 v83, v91, v91
	v_add_f32_e32 v82, v82, v94
	v_fmac_f32_e32 v83, v87, v87
	v_pk_add_f32 v[88:89], v[88:89], v[120:121]
	v_add_f32_e32 v82, v83, v82
	v_mul_f32_e32 v83, v92, v92
	v_fmac_f32_e32 v83, v88, v88
	v_add_f32_e32 v82, v83, v82
	v_mul_f32_e32 v83, v93, v93
	v_fmac_f32_e32 v83, v89, v89
	v_add_f32_e32 v82, v83, v82
	ds_bpermute_b32 v83, v169, v82
	v_lshlrev_b64 v[126:127], 11, v[176:177]
	v_lshl_add_u64 v[126:127], s[6:7], 0, v[126:127]
	v_lshl_add_u64 v[126:127], v[156:157], 1, v[126:127]
	v_readlane_b32 s64, v254, 38
	s_waitcnt lgkmcnt(0)
	v_add_f32_e32 v82, v82, v83
	ds_bpermute_b32 v83, v170, v82
	v_readlane_b32 s65, v254, 39
	v_readlane_b32 s66, v254, 40
	v_readlane_b32 s67, v254, 41
	v_readlane_b32 s68, v254, 42
	v_readlane_b32 s69, v254, 43
	v_readlane_b32 s70, v254, 44
	v_readlane_b32 s71, v254, 45
	v_readlane_b32 s72, v254, 46
	v_readlane_b32 s73, v254, 47
	v_readlane_b32 s74, v254, 48
	v_readlane_b32 s75, v254, 49
	global_store_dwordx4 v[126:127], v[122:125], off nt
	global_store_dwordx4 v[132:133], v[86:89], off offset:512 nt
	global_store_dwordx4 v[132:133], v[90:93], off offset:528 nt
	v_cvt_pk_bf16_f32 v84, v86, v87
	v_cvt_pk_bf16_f32 v85, v88, v89
	s_nop 0
	v_cvt_pk_bf16_f32 v86, v90, v91
	v_cvt_pk_bf16_f32 v87, v92, v93
	global_store_dwordx4 v[126:127], v[84:87], off offset:256 nt
	s_and_saveexec_b64 s[16:17], vcc
	s_cbranch_execz .LBB0_54
	v_lshl_add_u64 v[84:85], v[176:177], 2, s[8:9]
	s_waitcnt lgkmcnt(0)
	v_add_f32_e32 v82, v82, v83
	global_atomic_add_f32 v[84:85], v82, off
.LBB0_54:
	s_or_b64 exec, exec, s[16:17]
	v_readlane_b32 s60, v254, 34
	v_add_u32_e32 v114, 0x80, v158
	v_readlane_b32 s61, v254, 35
	v_readlane_b32 s63, v254, 37
	v_ashrrev_i32_e32 v115, 31, v114
	v_add_u32_e32 v82, 0xffffc080, v158
	v_cmp_gt_i32_e64 s[42:43], s85, v158
	v_readlane_b32 s62, v254, 36
	v_mov_b32_e32 v84, s63
	v_mov_b32_e32 v85, s61
	s_waitcnt lgkmcnt(0)
	v_cndmask_b32_e64 v83, 0, v115, s[42:43]
	v_cndmask_b32_e64 v82, v82, v114, s[42:43]
	v_cndmask_b32_e64 v85, v84, v85, s[42:43]
	v_mov_b32_e32 v84, s62
	v_mov_b32_e32 v86, s60
	v_cndmask_b32_e64 v84, v84, v86, s[42:43]
	v_lshlrev_b64 v[82:83], 12, v[82:83]
	v_lshl_add_u64 v[82:83], v[84:85], 0, v[82:83]
	v_lshl_add_u64 v[86:87], v[82:83], 0, v[160:161]
	global_load_dwordx4 v[90:93], v[86:87], off offset:16 nt
	global_load_dwordx4 v[94:97], v[86:87], off nt
	global_load_dwordx4 v[82:85], v[86:87], off offset:528 nt
	s_nop 0
	global_load_dwordx4 v[86:89], v[86:87], off offset:512 nt
	v_lshlrev_b64 v[116:117], 12, v[130:131]
	v_lshl_add_u64 v[116:117], s[22:23], 0, v[116:117]
	v_lshl_add_u64 v[116:117], v[116:117], 0, v[160:161]
	s_waitcnt vmcnt(12)
	v_pk_add_f32 v[80:81], v[80:81], v[112:113]
	v_pk_add_f32 v[78:79], v[78:79], v[110:111]
	v_pk_add_f32 v[74:75], v[74:75], v[106:107]
	v_pk_add_f32 v[76:77], v[76:77], v[108:109]
	global_store_dwordx4 v[116:117], v[78:81], off nt
	global_store_dwordx4 v[116:117], v[74:77], off offset:16 nt
	v_cvt_pk_bf16_f32 v106, v78, v79
	v_cvt_pk_bf16_f32 v107, v80, v81
	v_cvt_pk_bf16_f32 v108, v74, v75
	s_waitcnt vmcnt(12)
	v_pk_add_f32 v[70:71], v[70:71], v[102:103]
	v_cvt_pk_bf16_f32 v109, v76, v77
	v_mul_f32_e32 v74, v74, v74
	v_mul_f32_e32 v75, v75, v75
	v_fmac_f32_e32 v74, v78, v78
	v_fmac_f32_e32 v75, v79, v79
	v_add_f32_e32 v74, v74, v75
	v_mul_f32_e32 v75, v76, v76
	v_fmac_f32_e32 v75, v80, v80
	v_add_f32_e32 v74, v75, v74
	v_mul_f32_e32 v75, v77, v77
	v_fmac_f32_e32 v75, v81, v81
	v_add_f32_e32 v78, v75, v74
	v_pk_add_f32 v[74:75], v[66:67], v[98:99]
	v_pk_add_f32 v[76:77], v[68:69], v[100:101]
	v_mul_f32_e32 v66, v74, v74
	v_fmac_f32_e32 v66, v70, v70
	v_mul_f32_e32 v67, v75, v75
	v_add_f32_e32 v66, v66, v78
	v_fmac_f32_e32 v67, v71, v71
	v_pk_add_f32 v[72:73], v[72:73], v[104:105]
	v_add_f32_e32 v66, v67, v66
	v_mul_f32_e32 v67, v76, v76
	v_fmac_f32_e32 v67, v72, v72
	v_add_f32_e32 v66, v67, v66
	v_mul_f32_e32 v67, v77, v77
	v_fmac_f32_e32 v67, v73, v73
	v_add_f32_e32 v66, v67, v66
	ds_bpermute_b32 v67, v169, v66
	v_lshlrev_b64 v[110:111], 11, v[130:131]
	v_lshl_add_u64 v[110:111], s[6:7], 0, v[110:111]
	v_lshl_add_u64 v[110:111], v[156:157], 1, v[110:111]
	v_readlane_b32 s64, v254, 38
	s_waitcnt lgkmcnt(0)
	v_add_f32_e32 v66, v66, v67
	ds_bpermute_b32 v67, v170, v66
	v_readlane_b32 s65, v254, 39
	v_readlane_b32 s66, v254, 40
	v_readlane_b32 s67, v254, 41
	v_readlane_b32 s68, v254, 42
	v_readlane_b32 s69, v254, 43
	v_readlane_b32 s70, v254, 44
	v_readlane_b32 s71, v254, 45
	v_readlane_b32 s72, v254, 46
	v_readlane_b32 s73, v254, 47
	v_readlane_b32 s74, v254, 48
	v_readlane_b32 s75, v254, 49
	global_store_dwordx4 v[110:111], v[106:109], off nt
	global_store_dwordx4 v[116:117], v[70:73], off offset:512 nt
	global_store_dwordx4 v[116:117], v[74:77], off offset:528 nt
	v_cvt_pk_bf16_f32 v68, v70, v71
	v_cvt_pk_bf16_f32 v69, v72, v73
	s_nop 0
	v_cvt_pk_bf16_f32 v70, v74, v75
	v_cvt_pk_bf16_f32 v71, v76, v77
	global_store_dwordx4 v[110:111], v[68:71], off offset:256 nt
	s_and_saveexec_b64 s[16:17], vcc
	s_cbranch_execz .LBB0_56
	v_lshl_add_u64 v[68:69], v[130:131], 2, s[8:9]
	s_waitcnt lgkmcnt(0)
	v_add_f32_e32 v66, v66, v67
	global_atomic_add_f32 v[68:69], v66, off
; #define NTL(p) __builtin_nontemporal_load((const f32x4*)(p))
; #define NTS(v, p) __builtin_nontemporal_store((v), (f32x4*)(p))
; __device__ __forceinline__ unsigned cvt_pk_bf16(float lo, float hi) { unsigned r; asm volatile("v_cvt_pk_bf16_f32 %0, %1, %2" : "=v"(r) : "v"(lo), "v"(hi)); return r; }
;     __device__ __forceinline__ void operator()(AccT& acc, const Unit& u, int wr, int wc, int fr, int fq) const {
;     ...
;         for (int r = 0; r < 8; ++r) { const int ai = r >> 2, m = r & 3; const int row = row0 + ai * 128 + m * 16;
;             if (r < 7) { const int rn = row0 + ((r + 1) >> 2) * 128 + ((r + 1) & 3) * 16; const float* xr = (rn < HALF_TOK ? x0 + (size_t)rn * DM : x1 + (size_t)(rn - HALF_TOK) * DM) + col0;
;                 xv[(r + 1) & 1][0] = NTL(xr); xv[(r + 1) & 1][1] = NTL(xr + 4); xv[(r + 1) & 1][2] = NTL(xr + 128); xv[(r + 1) & 1][3] = NTL(xr + 132); }
;             float* hr = H + (size_t)row * DM + col0; float ss = 0.f;
; #pragma unroll
;             for (int bj = 0; bj < 2; ++bj) {
;                 f32x4 v0 = acc[ai][bj][m][0] + xv[r & 1][2 * bj], v1 = acc[ai][bj][m][1] + xv[r & 1][2 * bj + 1];
;                 NTS(v0, hr + bj * 128); NTS(v1, hr + bj * 128 + 4);
;                 u32x4 w; w.x = cvt_pk_bf16(v0[0], v0[1]); w.y = cvt_pk_bf16(v0[2], v0[3]); w.z = cvt_pk_bf16(v1[0], v1[1]); w.w = cvt_pk_bf16(v1[2], v1[3]);
;                 *(u32x4*)(HB + (size_t)row * DM + col0 + bj * 128) = w;
; #pragma unroll
;                 for (int j = 0; j < 4; ++j) ss += v0[j] * v0[j] + v1[j] * v1[j]; }
;             ss += __shfl_xor(ss, 16); ss += __shfl_xor(ss, 32);
;             if (fq == 0) unsafeAtomicAdd(rss + row, ss); __builtin_amdgcn_sched_barrier(0); }
.LBB0_56:
	s_or_b64 exec, exec, s[16:17]
	v_readlane_b32 s60, v254, 34
	v_add_u32_e32 v98, 0x90, v158
	v_readlane_b32 s61, v254, 35
	v_readlane_b32 s63, v254, 37
	v_ashrrev_i32_e32 v99, 31, v98
	v_add_u32_e32 v66, 0xffffc090, v158
	v_cmp_gt_i32_e64 s[42:43], s86, v158
	v_readlane_b32 s62, v254, 36
	v_mov_b32_e32 v68, s63
	v_mov_b32_e32 v69, s61
	s_waitcnt lgkmcnt(0)
	v_cndmask_b32_e64 v67, 0, v99, s[42:43]
	v_cndmask_b32_e64 v66, v66, v98, s[42:43]
	v_cndmask_b32_e64 v69, v68, v69, s[42:43]
	v_mov_b32_e32 v68, s62
	v_mov_b32_e32 v70, s60
	v_cndmask_b32_e64 v68, v68, v70, s[42:43]
	v_lshlrev_b64 v[66:67], 12, v[66:67]
	v_lshl_add_u64 v[66:67], v[68:69], 0, v[66:67]
	v_lshl_add_u64 v[70:71], v[66:67], 0, v[160:161]
	global_load_dwordx4 v[74:77], v[70:71], off offset:16 nt
	global_load_dwordx4 v[78:81], v[70:71], off nt
	global_load_dwordx4 v[66:69], v[70:71], off offset:528 nt
	s_nop 0
	global_load_dwordx4 v[70:73], v[70:71], off offset:512 nt
	v_lshlrev_b64 v[100:101], 12, v[114:115]
	v_lshl_add_u64 v[100:101], s[22:23], 0, v[100:101]
	v_lshl_add_u64 v[100:101], v[100:101], 0, v[160:161]
	s_waitcnt vmcnt(12)
	v_pk_add_f32 v[64:65], v[64:65], v[96:97]
	v_pk_add_f32 v[62:63], v[62:63], v[94:95]
	v_pk_add_f32 v[58:59], v[58:59], v[90:91]
	v_pk_add_f32 v[60:61], v[60:61], v[92:93]
	global_store_dwordx4 v[100:101], v[62:65], off nt
	global_store_dwordx4 v[100:101], v[58:61], off offset:16 nt
	v_cvt_pk_bf16_f32 v90, v62, v63
	v_cvt_pk_bf16_f32 v91, v64, v65
	v_cvt_pk_bf16_f32 v92, v58, v59
	s_waitcnt vmcnt(12)
	v_pk_add_f32 v[54:55], v[54:55], v[86:87]
	v_cvt_pk_bf16_f32 v93, v60, v61
	v_mul_f32_e32 v58, v58, v58
	v_mul_f32_e32 v59, v59, v59
	v_fmac_f32_e32 v58, v62, v62
	v_fmac_f32_e32 v59, v63, v63
	v_add_f32_e32 v58, v58, v59
	v_mul_f32_e32 v59, v60, v60
	v_fmac_f32_e32 v59, v64, v64
	v_add_f32_e32 v58, v59, v58
	v_mul_f32_e32 v59, v61, v61
	v_fmac_f32_e32 v59, v65, v65
	v_add_f32_e32 v62, v59, v58
	v_pk_add_f32 v[58:59], v[50:51], v[82:83]
	v_pk_add_f32 v[60:61], v[52:53], v[84:85]
	v_mul_f32_e32 v50, v58, v58
	v_fmac_f32_e32 v50, v54, v54
	v_mul_f32_e32 v51, v59, v59
	v_add_f32_e32 v50, v50, v62
	v_fmac_f32_e32 v51, v55, v55
	v_pk_add_f32 v[56:57], v[56:57], v[88:89]
	v_add_f32_e32 v50, v51, v50
	v_mul_f32_e32 v51, v60, v60
	v_fmac_f32_e32 v51, v56, v56
	v_add_f32_e32 v50, v51, v50
	v_mul_f32_e32 v51, v61, v61
	v_fmac_f32_e32 v51, v57, v57
	v_add_f32_e32 v50, v51, v50
	ds_bpermute_b32 v51, v169, v50
	v_lshlrev_b64 v[94:95], 11, v[114:115]
	v_lshl_add_u64 v[94:95], s[6:7], 0, v[94:95]
	v_lshl_add_u64 v[94:95], v[156:157], 1, v[94:95]
	v_readlane_b32 s64, v254, 38
	s_waitcnt lgkmcnt(0)
	v_add_f32_e32 v50, v50, v51
	ds_bpermute_b32 v51, v170, v50
	v_readlane_b32 s65, v254, 39
	v_readlane_b32 s66, v254, 40
	v_readlane_b32 s67, v254, 41
	v_readlane_b32 s68, v254, 42
	v_readlane_b32 s69, v254, 43
	v_readlane_b32 s70, v254, 44
	v_readlane_b32 s71, v254, 45
	v_readlane_b32 s72, v254, 46
	v_readlane_b32 s73, v254, 47
	v_readlane_b32 s74, v254, 48
	v_readlane_b32 s75, v254, 49
	global_store_dwordx4 v[94:95], v[90:93], off nt
	global_store_dwordx4 v[100:101], v[54:57], off offset:512 nt
	global_store_dwordx4 v[100:101], v[58:61], off offset:528 nt
	v_cvt_pk_bf16_f32 v52, v54, v55
	v_cvt_pk_bf16_f32 v53, v56, v57
	s_nop 0
	v_cvt_pk_bf16_f32 v54, v58, v59
	v_cvt_pk_bf16_f32 v55, v60, v61
	global_store_dwordx4 v[94:95], v[52:55], off offset:256 nt
	s_and_saveexec_b64 s[16:17], vcc
	s_cbranch_execz .LBB0_58
	v_lshl_add_u64 v[52:53], v[114:115], 2, s[8:9]
	s_waitcnt lgkmcnt(0)
	v_add_f32_e32 v50, v50, v51
	global_atomic_add_f32 v[52:53], v50, off
.LBB0_58:
	s_or_b64 exec, exec, s[16:17]
	v_readlane_b32 s60, v254, 34
	v_add_u32_e32 v82, 0xa0, v158
	v_readlane_b32 s61, v254, 35
	v_readlane_b32 s63, v254, 37
	v_ashrrev_i32_e32 v83, 31, v82
	v_add_u32_e32 v50, 0xffffc0a0, v158
	v_cmp_gt_i32_e64 s[42:43], s87, v158
	v_readlane_b32 s62, v254, 36
	v_mov_b32_e32 v52, s63
	v_mov_b32_e32 v53, s61
	s_waitcnt lgkmcnt(0)
	v_cndmask_b32_e64 v51, 0, v83, s[42:43]
	v_cndmask_b32_e64 v50, v50, v82, s[42:43]
	v_cndmask_b32_e64 v53, v52, v53, s[42:43]
	v_mov_b32_e32 v52, s62
	v_mov_b32_e32 v54, s60
	v_cndmask_b32_e64 v52, v52, v54, s[42:43]
	v_lshlrev_b64 v[50:51], 12, v[50:51]
	v_lshl_add_u64 v[50:51], v[52:53], 0, v[50:51]
	v_lshl_add_u64 v[54:55], v[50:51], 0, v[160:161]
	global_load_dwordx4 v[58:61], v[54:55], off offset:16 nt
	global_load_dwordx4 v[62:65], v[54:55], off nt
	global_load_dwordx4 v[50:53], v[54:55], off offset:528 nt
	s_nop 0
	global_load_dwordx4 v[54:57], v[54:55], off offset:512 nt
	v_lshlrev_b64 v[84:85], 12, v[98:99]
	v_lshl_add_u64 v[84:85], s[22:23], 0, v[84:85]
	v_lshl_add_u64 v[84:85], v[84:85], 0, v[160:161]
	s_waitcnt vmcnt(12)
	v_pk_add_f32 v[48:49], v[48:49], v[80:81]
	v_pk_add_f32 v[46:47], v[46:47], v[78:79]
	v_pk_add_f32 v[42:43], v[42:43], v[74:75]
	v_pk_add_f32 v[44:45], v[44:45], v[76:77]
	global_store_dwordx4 v[84:85], v[46:49], off nt
	global_store_dwordx4 v[84:85], v[42:45], off offset:16 nt
	v_cvt_pk_bf16_f32 v74, v46, v47
	v_cvt_pk_bf16_f32 v75, v48, v49
	v_cvt_pk_bf16_f32 v76, v42, v43
	s_waitcnt vmcnt(12)
	v_pk_add_f32 v[38:39], v[38:39], v[70:71]
	v_cvt_pk_bf16_f32 v77, v44, v45
	v_mul_f32_e32 v42, v42, v42
	v_mul_f32_e32 v43, v43, v43
	v_fmac_f32_e32 v42, v46, v46
	v_fmac_f32_e32 v43, v47, v47
	v_add_f32_e32 v42, v42, v43
	v_mul_f32_e32 v43, v44, v44
	v_fmac_f32_e32 v43, v48, v48
	v_add_f32_e32 v42, v43, v42
	v_mul_f32_e32 v43, v45, v45
	v_fmac_f32_e32 v43, v49, v49
	v_add_f32_e32 v46, v43, v42
	v_pk_add_f32 v[42:43], v[34:35], v[66:67]
	v_pk_add_f32 v[44:45], v[36:37], v[68:69]
	v_mul_f32_e32 v34, v42, v42
	v_fmac_f32_e32 v34, v38, v38
	v_mul_f32_e32 v35, v43, v43
	v_add_f32_e32 v34, v34, v46
	v_fmac_f32_e32 v35, v39, v39
	v_pk_add_f32 v[40:41], v[40:41], v[72:73]
	v_add_f32_e32 v34, v35, v34
	v_mul_f32_e32 v35, v44, v44
	v_fmac_f32_e32 v35, v40, v40
	v_add_f32_e32 v34, v35, v34
	v_mul_f32_e32 v35, v45, v45
	v_fmac_f32_e32 v35, v41, v41
	v_add_f32_e32 v34, v35, v34
	ds_bpermute_b32 v35, v169, v34
	v_lshlrev_b64 v[78:79], 11, v[98:99]
	v_lshl_add_u64 v[78:79], s[6:7], 0, v[78:79]
	v_lshl_add_u64 v[78:79], v[156:157], 1, v[78:79]
	v_readlane_b32 s64, v254, 38
	s_waitcnt lgkmcnt(0)
	v_add_f32_e32 v34, v34, v35
	ds_bpermute_b32 v35, v170, v34
	v_readlane_b32 s65, v254, 39
	v_readlane_b32 s66, v254, 40
	v_readlane_b32 s67, v254, 41
	v_readlane_b32 s68, v254, 42
	v_readlane_b32 s69, v254, 43
	v_readlane_b32 s70, v254, 44
	v_readlane_b32 s71, v254, 45
	v_readlane_b32 s72, v254, 46
	v_readlane_b32 s73, v254, 47
	v_readlane_b32 s74, v254, 48
	v_readlane_b32 s75, v254, 49
	global_store_dwordx4 v[78:79], v[74:77], off nt
	global_store_dwordx4 v[84:85], v[38:41], off offset:512 nt
	global_store_dwordx4 v[84:85], v[42:45], off offset:528 nt
	v_cvt_pk_bf16_f32 v36, v38, v39
	v_cvt_pk_bf16_f32 v37, v40, v41
	s_nop 0
	v_cvt_pk_bf16_f32 v38, v42, v43
	v_cvt_pk_bf16_f32 v39, v44, v45
	global_store_dwordx4 v[78:79], v[36:39], off offset:256 nt
	s_and_saveexec_b64 s[16:17], vcc
	s_cbranch_execz .LBB0_60
; #define NTL(p) __builtin_nontemporal_load((const f32x4*)(p))
; #define NTS(v, p) __builtin_nontemporal_store((v), (f32x4*)(p))
; __device__ __forceinline__ unsigned cvt_pk_bf16(float lo, float hi) { unsigned r; asm volatile("v_cvt_pk_bf16_f32 %0, %1, %2" : "=v"(r) : "v"(lo), "v"(hi)); return r; }
;     __device__ __forceinline__ void operator()(AccT& acc, const Unit& u, int wr, int wc, int fr, int fq) const {
;     ...
;         for (int r = 0; r < 8; ++r) { const int ai = r >> 2, m = r & 3; const int row = row0 + ai * 128 + m * 16;
;             if (r < 7) { const int rn = row0 + ((r + 1) >> 2) * 128 + ((r + 1) & 3) * 16; const float* xr = (rn < HALF_TOK ? x0 + (size_t)rn * DM : x1 + (size_t)(rn - HALF_TOK) * DM) + col0;
;                 xv[(r + 1) & 1][0] = NTL(xr); xv[(r + 1) & 1][1] = NTL(xr + 4); xv[(r + 1) & 1][2] = NTL(xr + 128); xv[(r + 1) & 1][3] = NTL(xr + 132); }
;             float* hr = H + (size_t)row * DM + col0; float ss = 0.f;
; #pragma unroll
;             for (int bj = 0; bj < 2; ++bj) {
;                 f32x4 v0 = acc[ai][bj][m][0] + xv[r & 1][2 * bj], v1 = acc[ai][bj][m][1] + xv[r & 1][2 * bj + 1];
;                 NTS(v0, hr + bj * 128); NTS(v1, hr + bj * 128 + 4);
;                 u32x4 w; w.x = cvt_pk_bf16(v0[0], v0[1]); w.y = cvt_pk_bf16(v0[2], v0[3]); w.z = cvt_pk_bf16(v1[0], v1[1]); w.w = cvt_pk_bf16(v1[2], v1[3]);
;                 *(u32x4*)(HB + (size_t)row * DM + col0 + bj * 128) = w;
; #pragma unroll
;                 for (int j = 0; j < 4; ++j) ss += v0[j] * v0[j] + v1[j] * v1[j]; }
;             ss += __shfl_xor(ss, 16); ss += __shfl_xor(ss, 32);
;             if (fq == 0) unsafeAtomicAdd(rss + row, ss); __builtin_amdgcn_sched_barrier(0); }
	v_lshl_add_u64 v[36:37], v[98:99], 2, s[8:9]
	s_waitcnt lgkmcnt(0)
	v_add_f32_e32 v34, v34, v35
	global_atomic_add_f32 v[36:37], v34, off
.LBB0_60:
	s_or_b64 exec, exec, s[16:17]
	v_readlane_b32 s60, v254, 34
	v_add_u32_e32 v66, 0xb0, v158
	v_readlane_b32 s61, v254, 35
	v_readlane_b32 s63, v254, 37
	v_ashrrev_i32_e32 v67, 31, v66
	v_add_u32_e32 v34, 0xffffc0b0, v158
	v_cmp_gt_i32_e64 s[42:43], s88, v158
	v_readlane_b32 s62, v254, 36
	v_mov_b32_e32 v36, s63
	v_mov_b32_e32 v37, s61
	s_waitcnt lgkmcnt(0)
	v_cndmask_b32_e64 v35, 0, v67, s[42:43]
	v_cndmask_b32_e64 v34, v34, v66, s[42:43]
	v_cndmask_b32_e64 v37, v36, v37, s[42:43]
	v_mov_b32_e32 v36, s62
	v_mov_b32_e32 v38, s60
	v_cndmask_b32_e64 v36, v36, v38, s[42:43]
	v_lshlrev_b64 v[34:35], 12, v[34:35]
	v_lshl_add_u64 v[34:35], v[36:37], 0, v[34:35]
	v_lshl_add_u64 v[38:39], v[34:35], 0, v[160:161]
	global_load_dwordx4 v[42:45], v[38:39], off offset:16 nt
	global_load_dwordx4 v[46:49], v[38:39], off nt
	global_load_dwordx4 v[34:37], v[38:39], off offset:528 nt
	s_nop 0
	global_load_dwordx4 v[38:41], v[38:39], off offset:512 nt
	v_lshlrev_b64 v[68:69], 12, v[82:83]
	v_lshl_add_u64 v[68:69], s[22:23], 0, v[68:69]
	v_lshl_add_u64 v[68:69], v[68:69], 0, v[160:161]
	s_waitcnt vmcnt(12)
	v_pk_add_f32 v[32:33], v[32:33], v[64:65]
	v_pk_add_f32 v[30:31], v[30:31], v[62:63]
	v_pk_add_f32 v[26:27], v[26:27], v[58:59]
	v_pk_add_f32 v[28:29], v[28:29], v[60:61]
	global_store_dwordx4 v[68:69], v[30:33], off nt
	global_store_dwordx4 v[68:69], v[26:29], off offset:16 nt
	v_cvt_pk_bf16_f32 v58, v30, v31
	v_cvt_pk_bf16_f32 v59, v32, v33
	v_cvt_pk_bf16_f32 v60, v26, v27
	s_waitcnt vmcnt(12)
	v_pk_add_f32 v[22:23], v[22:23], v[54:55]
	v_cvt_pk_bf16_f32 v61, v28, v29
	v_mul_f32_e32 v26, v26, v26
	v_mul_f32_e32 v27, v27, v27
	v_fmac_f32_e32 v26, v30, v30
	v_fmac_f32_e32 v27, v31, v31
	v_add_f32_e32 v26, v26, v27
	v_mul_f32_e32 v27, v28, v28
	v_fmac_f32_e32 v27, v32, v32
	v_add_f32_e32 v26, v27, v26
	v_mul_f32_e32 v27, v29, v29
	v_fmac_f32_e32 v27, v33, v33
	v_add_f32_e32 v30, v27, v26
	v_pk_add_f32 v[26:27], v[18:19], v[50:51]
	v_pk_add_f32 v[28:29], v[20:21], v[52:53]
	v_mul_f32_e32 v18, v26, v26
	v_fmac_f32_e32 v18, v22, v22
	v_mul_f32_e32 v19, v27, v27
	v_add_f32_e32 v18, v18, v30
	v_fmac_f32_e32 v19, v23, v23
	v_pk_add_f32 v[24:25], v[24:25], v[56:57]
	v_add_f32_e32 v18, v19, v18
	v_mul_f32_e32 v19, v28, v28
	v_fmac_f32_e32 v19, v24, v24
	v_add_f32_e32 v18, v19, v18
	v_mul_f32_e32 v19, v29, v29
	v_fmac_f32_e32 v19, v25, v25
	v_add_f32_e32 v18, v19, v18
	ds_bpermute_b32 v19, v169, v18
	v_lshlrev_b64 v[62:63], 11, v[82:83]
	v_lshl_add_u64 v[62:63], s[6:7], 0, v[62:63]
	v_lshl_add_u64 v[62:63], v[156:157], 1, v[62:63]
	v_readlane_b32 s64, v254, 38
	s_waitcnt lgkmcnt(0)
	v_add_f32_e32 v18, v18, v19
	ds_bpermute_b32 v19, v170, v18
	v_readlane_b32 s65, v254, 39
	v_readlane_b32 s66, v254, 40
	v_readlane_b32 s67, v254, 41
	v_readlane_b32 s68, v254, 42
	v_readlane_b32 s69, v254, 43
	v_readlane_b32 s70, v254, 44
	v_readlane_b32 s71, v254, 45
	v_readlane_b32 s72, v254, 46
	v_readlane_b32 s73, v254, 47
	v_readlane_b32 s74, v254, 48
	v_readlane_b32 s75, v254, 49
	global_store_dwordx4 v[62:63], v[58:61], off nt
	global_store_dwordx4 v[68:69], v[22:25], off offset:512 nt
	global_store_dwordx4 v[68:69], v[26:29], off offset:528 nt
	v_cvt_pk_bf16_f32 v20, v22, v23
	v_cvt_pk_bf16_f32 v21, v24, v25
	s_nop 0
	v_cvt_pk_bf16_f32 v22, v26, v27
	v_cvt_pk_bf16_f32 v23, v28, v29
	global_store_dwordx4 v[62:63], v[20:23], off offset:256 nt
	s_and_saveexec_b64 s[16:17], vcc
	s_cbranch_execz .LBB0_62
	v_lshl_add_u64 v[20:21], v[82:83], 2, s[8:9]
	s_waitcnt lgkmcnt(0)
	v_add_f32_e32 v18, v18, v19
	global_atomic_add_f32 v[20:21], v18, off
.LBB0_62:
	s_or_b64 exec, exec, s[16:17]
	s_waitcnt lgkmcnt(0)
	v_lshlrev_b64 v[18:19], 12, v[66:67]
	v_lshl_add_u64 v[18:19], s[22:23], 0, v[18:19]
	v_lshl_add_u64 v[22:23], v[156:157], 2, v[18:19]
	s_waitcnt vmcnt(8)
	v_pk_add_f32 v[16:17], v[16:17], v[48:49]
	v_pk_add_f32 v[14:15], v[14:15], v[46:47]
	v_pk_add_f32 v[10:11], v[10:11], v[42:43]
	v_pk_add_f32 v[12:13], v[12:13], v[44:45]
	global_store_dwordx4 v[22:23], v[14:17], off nt
	global_store_dwordx4 v[22:23], v[10:13], off offset:16 nt
	v_cvt_pk_bf16_f32 v18, v14, v15
	v_cvt_pk_bf16_f32 v19, v16, v17
	v_cvt_pk_bf16_f32 v20, v10, v11
	s_waitcnt vmcnt(8)
	v_pk_add_f32 v[6:7], v[6:7], v[38:39]
	v_cvt_pk_bf16_f32 v21, v12, v13
	v_mul_f32_e32 v10, v10, v10
	v_mul_f32_e32 v11, v11, v11
	v_fmac_f32_e32 v10, v14, v14
	v_fmac_f32_e32 v11, v15, v15
	v_add_f32_e32 v10, v10, v11
	v_mul_f32_e32 v11, v12, v12
	v_fmac_f32_e32 v11, v16, v16
	v_add_f32_e32 v10, v11, v10
	v_mul_f32_e32 v11, v13, v13
	v_fmac_f32_e32 v11, v17, v17
	v_add_f32_e32 v14, v11, v10
	v_pk_add_f32 v[10:11], v[2:3], v[34:35]
	v_pk_add_f32 v[12:13], v[4:5], v[36:37]
	v_mul_f32_e32 v2, v10, v10
	v_fmac_f32_e32 v2, v6, v6
	v_mul_f32_e32 v3, v11, v11
	v_add_f32_e32 v2, v2, v14
	v_fmac_f32_e32 v3, v7, v7
	v_pk_add_f32 v[8:9], v[8:9], v[40:41]
	v_add_f32_e32 v2, v3, v2
	v_mul_f32_e32 v3, v12, v12
	v_fmac_f32_e32 v3, v8, v8
	v_add_f32_e32 v2, v3, v2
	v_mul_f32_e32 v3, v13, v13
	v_fmac_f32_e32 v3, v9, v9
	v_add_f32_e32 v2, v3, v2
	ds_bpermute_b32 v3, v169, v2
	v_lshlrev_b64 v[24:25], 11, v[66:67]
	v_lshl_add_u64 v[24:25], s[6:7], 0, v[24:25]
	v_lshl_add_u64 v[24:25], v[156:157], 1, v[24:25]
	global_store_dwordx4 v[24:25], v[18:21], off nt
	global_store_dwordx4 v[22:23], v[6:9], off offset:512 nt
	global_store_dwordx4 v[22:23], v[10:13], off offset:528 nt
	s_waitcnt lgkmcnt(0)
	v_add_f32_e32 v2, v2, v3
	ds_bpermute_b32 v3, v170, v2
	v_cvt_pk_bf16_f32 v4, v6, v7
	v_cvt_pk_bf16_f32 v5, v8, v9
	v_cvt_pk_bf16_f32 v6, v10, v11
	v_cvt_pk_bf16_f32 v7, v12, v13
	global_store_dwordx4 v[24:25], v[4:7], off offset:256 nt
	s_and_saveexec_b64 s[16:17], vcc
	s_cbranch_execz .LBB0_34
	v_lshl_add_u64 v[4:5], v[66:67], 2, s[8:9]
	s_waitcnt lgkmcnt(0)
	v_add_f32_e32 v2, v2, v3
	global_atomic_add_f32 v[4:5], v2, off
	s_branch .LBB0_34

; #define NTL(p) __builtin_nontemporal_load((const f32x4*)(p))
; #define NTS(v, p) __builtin_nontemporal_store((v), (f32x4*)(p))
; __device__ __forceinline__ unsigned cvt_pk_bf16(float lo, float hi) { unsigned r; asm volatile("v_cvt_pk_bf16_f32 %0, %1, %2" : "=v"(r) : "v"(lo), "v"(hi)); return r; }
;     __device__ __forceinline__ void operator()(AccT& acc, const Unit& u, int wr, int wc, int fr, int fq) const {
;     ...
;         for (int r = 0; r < 8; ++r) { const int ai = r >> 2, m = r & 3; const int row = row0 + ai * 128 + m * 16;
;             if (r < 7) { const int rn = row0 + ((r + 1) >> 2) * 128 + ((r + 1) & 3) * 16; const float* hn = H + (size_t)rn * DM + col0;
;                 hv[(r + 1) & 1][0] = NTL(hn); hv[(r + 1) & 1][1] = NTL(hn + 4); hv[(r + 1) & 1][2] = NTL(hn + 128); hv[(r + 1) & 1][3] = NTL(hn + 132); }
;             float* hr = H + (size_t)row * DM + col0; float ss = 0.f;
; #pragma unroll
;             for (int bj = 0; bj < 2; ++bj) {
;                 f32x4 v0 = acc[ai][bj][m][0] + hv[r & 1][2 * bj], v1 = acc[ai][bj][m][1] + hv[r & 1][2 * bj + 1];
;                 NTS(v0, hr + bj * 128); NTS(v1, hr + bj * 128 + 4);
;                 u32x4 w; w.x = cvt_pk_bf16(v0[0], v0[1]); w.y = cvt_pk_bf16(v0[2], v0[3]); w.z = cvt_pk_bf16(v1[0], v1[1]); w.w = cvt_pk_bf16(v1[2], v1[3]);
;                 *(u32x4*)(HB + (size_t)row * DM + col0 + bj * 128) = w;
; #pragma unroll
;                 for (int j = 0; j < 4; ++j) ss += v0[j] * v0[j] + v1[j] * v1[j]; }
;             ss += __shfl_xor(ss, 16); ss += __shfl_xor(ss, 32);
;             if (fq == 0) unsafeAtomicAdd(rss + row, ss); __builtin_amdgcn_sched_barrier(0); }
.LBB0_851:
	s_lshl_b32 s16, s75, 8
	v_mov_b32_e32 v130, v164
	s_add_i32 s16, s57, s16
	v_mov_b32_e32 v134, v165
	v_add_u32_e32 v158, s16, v130
	s_lshl_b32 s16, s76, 8
	s_or_b32 s16, s16, s54
	v_ashrrev_i32_e32 v159, 31, v158
	v_lshl_add_u32 v156, v134, 3, s16
	v_lshlrev_b64 v[130:131], 12, v[158:159]
	v_ashrrev_i32_e32 v157, 31, v156
	v_lshl_add_u64 v[130:131], s[22:23], 0, v[130:131]
	v_lshlrev_b64 v[132:133], 2, v[156:157]
	v_lshl_add_u64 v[188:189], v[130:131], 0, v[132:133]
	global_load_dwordx4 v[170:173], v[188:189], off offset:16 nt
	global_load_dwordx4 v[176:179], v[188:189], off nt
	global_load_dwordx4 v[180:183], v[188:189], off offset:528 nt
	global_load_dwordx4 v[184:187], v[188:189], off offset:512 nt
	v_add_u32_e32 v160, 16, v158
	v_ashrrev_i32_e32 v161, 31, v160
	v_lshlrev_b64 v[130:131], 12, v[160:161]
	v_lshl_add_u64 v[130:131], s[22:23], 0, v[130:131]
	v_lshl_add_u64 v[174:175], v[130:131], 0, v[132:133]
	v_cmp_eq_u32_e32 vcc, 0, v134
	global_load_dwordx4 v[138:141], v[174:175], off offset:16 nt
	global_load_dwordx4 v[142:145], v[174:175], off nt
	global_load_dwordx4 v[130:133], v[174:175], off offset:528 nt
	global_load_dwordx4 v[134:137], v[174:175], off offset:512 nt
	s_waitcnt vmcnt(0)
	v_pk_add_f32 v[126:127], v[126:127], v[170:171]
	v_pk_add_f32 v[124:125], v[124:125], v[178:179]
	v_pk_add_f32 v[122:123], v[122:123], v[176:177]
	v_pk_add_f32 v[128:129], v[128:129], v[172:173]
	global_store_dwordx4 v[188:189], v[122:125], off nt
	global_store_dwordx4 v[188:189], v[126:129], off offset:16 nt
	v_cvt_pk_bf16_f32 v170, v122, v123
	v_cvt_pk_bf16_f32 v171, v124, v125
	v_cvt_pk_bf16_f32 v172, v126, v127
	v_lshlrev_b64 v[176:177], 11, v[158:159]
	v_lshl_add_u64 v[176:177], s[2:3], 0, v[176:177]
	v_mul_f32_e32 v126, v126, v126
	v_fmac_f32_e32 v126, v122, v122
	v_mul_f32_e32 v122, v127, v127
	v_fmac_f32_e32 v122, v123, v123
	v_mul_f32_e32 v123, v128, v128
	v_add_f32_e32 v122, v126, v122
	v_fmac_f32_e32 v123, v124, v124
	v_add_f32_e32 v122, v123, v122
	v_mul_f32_e32 v123, v129, v129
	v_lshl_add_u64 v[176:177], v[156:157], 1, v[176:177]
	v_fmac_f32_e32 v123, v125, v125
	v_pk_add_f32 v[120:121], v[120:121], v[186:187]
	v_pk_add_f32 v[118:119], v[118:119], v[184:185]
	v_pk_add_f32 v[114:115], v[114:115], v[180:181]
	v_cvt_pk_bf16_f32 v173, v128, v129
	global_store_dwordx4 v[176:177], v[170:173], off nt
	v_add_f32_e32 v126, v123, v122
	v_pk_add_f32 v[116:117], v[116:117], v[182:183]
	global_store_dwordx4 v[188:189], v[118:121], off offset:512 nt
	global_store_dwordx4 v[188:189], v[114:117], off offset:528 nt
	v_cvt_pk_bf16_f32 v122, v118, v119
	v_cvt_pk_bf16_f32 v123, v120, v121
	v_cvt_pk_bf16_f32 v124, v114, v115
	v_cvt_pk_bf16_f32 v125, v116, v117
	global_store_dwordx4 v[176:177], v[122:125], off offset:256 nt
	s_nop 0
	v_mul_f32_e32 v114, v114, v114
	v_fmac_f32_e32 v114, v118, v118
	v_mul_f32_e32 v115, v115, v115
	v_add_f32_e32 v114, v114, v126
	v_fmac_f32_e32 v115, v119, v119
	v_add_f32_e32 v114, v115, v114
	v_mul_f32_e32 v115, v116, v116
	v_fmac_f32_e32 v115, v120, v120
	v_add_f32_e32 v114, v115, v114
	v_mul_f32_e32 v115, v117, v117
	v_fmac_f32_e32 v115, v121, v121
	v_and_b32_e32 v116, 64, v203
	v_add_f32_e32 v114, v115, v114
	v_xor_b32_e32 v115, 16, v203
	v_add_u32_e32 v116, 64, v116
	v_cmp_lt_i32_e64 s[42:43], v115, v116
	s_nop 1
	v_cndmask_b32_e64 v115, v203, v115, s[42:43]
	v_lshlrev_b32_e32 v169, 2, v115
	ds_bpermute_b32 v115, v169, v114
	s_waitcnt lgkmcnt(0)
	v_add_f32_e32 v114, v114, v115
	v_xor_b32_e32 v115, 32, v203
	v_cmp_lt_i32_e64 s[42:43], v115, v116
	s_nop 1
	v_cndmask_b32_e64 v115, v203, v115, s[42:43]
	v_lshlrev_b32_e32 v170, 2, v115
	ds_bpermute_b32 v115, v170, v114
	s_and_saveexec_b64 s[16:17], vcc
	s_cbranch_execz .LBB0_853
	v_lshl_add_u64 v[116:117], v[158:159], 2, s[8:9]
	s_waitcnt lgkmcnt(0)
	v_add_f32_e32 v114, v114, v115
	global_atomic_add_f32 v[116:117], v114, off
.LBB0_853:
	s_or_b64 exec, exec, s[16:17]
	v_add_u32_e32 v176, 32, v158
	v_ashrrev_i32_e32 v177, 31, v176
	s_waitcnt lgkmcnt(0)
	v_lshlrev_b64 v[114:115], 12, v[176:177]
	v_lshl_add_u64 v[114:115], s[22:23], 0, v[114:115]
	v_lshl_add_u64 v[178:179], v[156:157], 2, v[114:115]
	global_load_dwordx4 v[122:125], v[178:179], off offset:16 nt
	global_load_dwordx4 v[126:129], v[178:179], off nt
	global_load_dwordx4 v[114:117], v[178:179], off offset:528 nt
	global_load_dwordx4 v[118:121], v[178:179], off offset:512 nt
	v_pk_add_f32 v[112:113], v[112:113], v[144:145]
	v_pk_add_f32 v[110:111], v[110:111], v[142:143]
	v_pk_add_f32 v[106:107], v[106:107], v[138:139]
	v_pk_add_f32 v[108:109], v[108:109], v[140:141]
	global_store_dwordx4 v[174:175], v[110:113], off nt
	global_store_dwordx4 v[174:175], v[106:109], off offset:16 nt
	v_cvt_pk_bf16_f32 v138, v110, v111
	v_cvt_pk_bf16_f32 v139, v112, v113
	v_cvt_pk_bf16_f32 v140, v106, v107
	v_pk_add_f32 v[102:103], v[102:103], v[134:135]
	v_cvt_pk_bf16_f32 v141, v108, v109
	s_nop 0
	v_mul_f32_e32 v106, v106, v106
	v_mul_f32_e32 v107, v107, v107
	v_fmac_f32_e32 v106, v110, v110
	v_fmac_f32_e32 v107, v111, v111
	v_add_f32_e32 v106, v106, v107
	v_mul_f32_e32 v107, v108, v108
	v_fmac_f32_e32 v107, v112, v112
	v_add_f32_e32 v106, v107, v106
	v_mul_f32_e32 v107, v109, v109
	v_fmac_f32_e32 v107, v113, v113
	v_add_f32_e32 v110, v107, v106
	v_pk_add_f32 v[106:107], v[98:99], v[130:131]
	v_pk_add_f32 v[108:109], v[100:101], v[132:133]
	v_mul_f32_e32 v98, v106, v106
	v_fmac_f32_e32 v98, v102, v102
	v_mul_f32_e32 v99, v107, v107
	v_add_f32_e32 v98, v98, v110
	v_fmac_f32_e32 v99, v103, v103
	v_pk_add_f32 v[104:105], v[104:105], v[136:137]
	v_add_f32_e32 v98, v99, v98
	v_mul_f32_e32 v99, v108, v108
	v_fmac_f32_e32 v99, v104, v104
	v_add_f32_e32 v98, v99, v98
	v_mul_f32_e32 v99, v109, v109
	v_fmac_f32_e32 v99, v105, v105
	v_add_f32_e32 v98, v99, v98
	ds_bpermute_b32 v99, v169, v98
	v_lshlrev_b64 v[142:143], 11, v[160:161]
	v_lshl_add_u64 v[142:143], s[2:3], 0, v[142:143]
	v_lshl_add_u64 v[142:143], v[156:157], 1, v[142:143]
	global_store_dwordx4 v[142:143], v[138:141], off nt
	global_store_dwordx4 v[174:175], v[102:105], off offset:512 nt
	global_store_dwordx4 v[174:175], v[106:109], off offset:528 nt
	s_waitcnt lgkmcnt(0)
	v_add_f32_e32 v98, v98, v99
	ds_bpermute_b32 v99, v170, v98
	v_cvt_pk_bf16_f32 v100, v102, v103
	v_cvt_pk_bf16_f32 v101, v104, v105
	v_cvt_pk_bf16_f32 v102, v106, v107
	v_cvt_pk_bf16_f32 v103, v108, v109
	global_store_dwordx4 v[142:143], v[100:103], off offset:256 nt
	s_and_saveexec_b64 s[16:17], vcc
	s_cbranch_execz .LBB0_855
	v_lshl_add_u64 v[100:101], v[160:161], 2, s[8:9]
	s_waitcnt lgkmcnt(0)
	v_add_f32_e32 v98, v98, v99
	global_atomic_add_f32 v[100:101], v98, off
; #define NTL(p) __builtin_nontemporal_load((const f32x4*)(p))
; #define NTS(v, p) __builtin_nontemporal_store((v), (f32x4*)(p))
; __device__ __forceinline__ unsigned cvt_pk_bf16(float lo, float hi) { unsigned r; asm volatile("v_cvt_pk_bf16_f32 %0, %1, %2" : "=v"(r) : "v"(lo), "v"(hi)); return r; }
;     __device__ __forceinline__ void operator()(AccT& acc, const Unit& u, int wr, int wc, int fr, int fq) const {
;     ...
;         for (int r = 0; r < 8; ++r) { const int ai = r >> 2, m = r & 3; const int row = row0 + ai * 128 + m * 16;
;             if (r < 7) { const int rn = row0 + ((r + 1) >> 2) * 128 + ((r + 1) & 3) * 16; const float* hn = H + (size_t)rn * DM + col0;
;                 hv[(r + 1) & 1][0] = NTL(hn); hv[(r + 1) & 1][1] = NTL(hn + 4); hv[(r + 1) & 1][2] = NTL(hn + 128); hv[(r + 1) & 1][3] = NTL(hn + 132); }
;             float* hr = H + (size_t)row * DM + col0; float ss = 0.f;
; #pragma unroll
;             for (int bj = 0; bj < 2; ++bj) {
;                 f32x4 v0 = acc[ai][bj][m][0] + hv[r & 1][2 * bj], v1 = acc[ai][bj][m][1] + hv[r & 1][2 * bj + 1];
;                 NTS(v0, hr + bj * 128); NTS(v1, hr + bj * 128 + 4);
;                 u32x4 w; w.x = cvt_pk_bf16(v0[0], v0[1]); w.y = cvt_pk_bf16(v0[2], v0[3]); w.z = cvt_pk_bf16(v1[0], v1[1]); w.w = cvt_pk_bf16(v1[2], v1[3]);
;                 *(u32x4*)(HB + (size_t)row * DM + col0 + bj * 128) = w;
; #pragma unroll
;                 for (int j = 0; j < 4; ++j) ss += v0[j] * v0[j] + v1[j] * v1[j]; }
;             ss += __shfl_xor(ss, 16); ss += __shfl_xor(ss, 32);
;             if (fq == 0) unsafeAtomicAdd(rss + row, ss); __builtin_amdgcn_sched_barrier(0); }
.LBB0_855:
	s_or_b64 exec, exec, s[16:17]
	v_add_u32_e32 v130, 48, v158
	v_ashrrev_i32_e32 v131, 31, v130
	s_waitcnt lgkmcnt(0)
	v_lshlrev_b64 v[98:99], 12, v[130:131]
	v_lshl_add_u64 v[98:99], s[22:23], 0, v[98:99]
	v_lshl_add_u64 v[132:133], v[156:157], 2, v[98:99]
	global_load_dwordx4 v[106:109], v[132:133], off offset:16 nt
	global_load_dwordx4 v[110:113], v[132:133], off nt
	global_load_dwordx4 v[98:101], v[132:133], off offset:528 nt
	global_load_dwordx4 v[102:105], v[132:133], off offset:512 nt
	s_waitcnt vmcnt(12)
	v_pk_add_f32 v[96:97], v[96:97], v[128:129]
	v_pk_add_f32 v[94:95], v[94:95], v[126:127]
	v_pk_add_f32 v[90:91], v[90:91], v[122:123]
	v_pk_add_f32 v[92:93], v[92:93], v[124:125]
	global_store_dwordx4 v[178:179], v[94:97], off nt
	global_store_dwordx4 v[178:179], v[90:93], off offset:16 nt
	v_cvt_pk_bf16_f32 v122, v94, v95
	v_cvt_pk_bf16_f32 v123, v96, v97
	v_cvt_pk_bf16_f32 v124, v90, v91
	s_waitcnt vmcnt(12)
	v_pk_add_f32 v[86:87], v[86:87], v[118:119]
	v_cvt_pk_bf16_f32 v125, v92, v93
	v_mul_f32_e32 v90, v90, v90
	v_mul_f32_e32 v91, v91, v91
	v_fmac_f32_e32 v90, v94, v94
	v_fmac_f32_e32 v91, v95, v95
	v_add_f32_e32 v90, v90, v91
	v_mul_f32_e32 v91, v92, v92
	v_fmac_f32_e32 v91, v96, v96
	v_add_f32_e32 v90, v91, v90
	v_mul_f32_e32 v91, v93, v93
	v_fmac_f32_e32 v91, v97, v97
	v_add_f32_e32 v94, v91, v90
	v_pk_add_f32 v[90:91], v[82:83], v[114:115]
	v_pk_add_f32 v[92:93], v[84:85], v[116:117]
	v_mul_f32_e32 v82, v90, v90
	v_fmac_f32_e32 v82, v86, v86
	v_mul_f32_e32 v83, v91, v91
	v_add_f32_e32 v82, v82, v94
	v_fmac_f32_e32 v83, v87, v87
	v_pk_add_f32 v[88:89], v[88:89], v[120:121]
	v_add_f32_e32 v82, v83, v82
	v_mul_f32_e32 v83, v92, v92
	v_fmac_f32_e32 v83, v88, v88
	v_add_f32_e32 v82, v83, v82
	v_mul_f32_e32 v83, v93, v93
	v_fmac_f32_e32 v83, v89, v89
	v_add_f32_e32 v82, v83, v82
	ds_bpermute_b32 v83, v169, v82
	v_lshlrev_b64 v[126:127], 11, v[176:177]
	v_lshl_add_u64 v[126:127], s[2:3], 0, v[126:127]
	v_lshl_add_u64 v[126:127], v[156:157], 1, v[126:127]
	global_store_dwordx4 v[126:127], v[122:125], off nt
	global_store_dwordx4 v[178:179], v[86:89], off offset:512 nt
	global_store_dwordx4 v[178:179], v[90:93], off offset:528 nt
	s_waitcnt lgkmcnt(0)
	v_add_f32_e32 v82, v82, v83
	ds_bpermute_b32 v83, v170, v82
	v_cvt_pk_bf16_f32 v84, v86, v87
	v_cvt_pk_bf16_f32 v85, v88, v89
	v_cvt_pk_bf16_f32 v86, v90, v91
	v_cvt_pk_bf16_f32 v87, v92, v93
	global_store_dwordx4 v[126:127], v[84:87], off offset:256 nt
	s_and_saveexec_b64 s[16:17], vcc
	s_cbranch_execz .LBB0_857
	v_lshl_add_u64 v[84:85], v[176:177], 2, s[8:9]
	s_waitcnt lgkmcnt(0)
	v_add_f32_e32 v82, v82, v83
	global_atomic_add_f32 v[84:85], v82, off
.LBB0_857:
	s_or_b64 exec, exec, s[16:17]
	v_add_u32_e32 v114, 0x80, v158
	v_ashrrev_i32_e32 v115, 31, v114
	s_waitcnt lgkmcnt(0)
	v_lshlrev_b64 v[82:83], 12, v[114:115]
	v_lshl_add_u64 v[82:83], s[22:23], 0, v[82:83]
	v_lshl_add_u64 v[116:117], v[156:157], 2, v[82:83]
	global_load_dwordx4 v[90:93], v[116:117], off offset:16 nt
	global_load_dwordx4 v[94:97], v[116:117], off nt
	global_load_dwordx4 v[82:85], v[116:117], off offset:528 nt
	global_load_dwordx4 v[86:89], v[116:117], off offset:512 nt
	s_waitcnt vmcnt(12)
	v_pk_add_f32 v[80:81], v[80:81], v[112:113]
	v_pk_add_f32 v[78:79], v[78:79], v[110:111]
	v_pk_add_f32 v[74:75], v[74:75], v[106:107]
	v_pk_add_f32 v[76:77], v[76:77], v[108:109]
	global_store_dwordx4 v[132:133], v[78:81], off nt
	global_store_dwordx4 v[132:133], v[74:77], off offset:16 nt
	v_cvt_pk_bf16_f32 v106, v78, v79
	v_cvt_pk_bf16_f32 v107, v80, v81
	v_cvt_pk_bf16_f32 v108, v74, v75
	s_waitcnt vmcnt(12)
	v_pk_add_f32 v[70:71], v[70:71], v[102:103]
	v_cvt_pk_bf16_f32 v109, v76, v77
	v_mul_f32_e32 v74, v74, v74
	v_mul_f32_e32 v75, v75, v75
	v_fmac_f32_e32 v74, v78, v78
	v_fmac_f32_e32 v75, v79, v79
	v_add_f32_e32 v74, v74, v75
	v_mul_f32_e32 v75, v76, v76
	v_fmac_f32_e32 v75, v80, v80
	v_add_f32_e32 v74, v75, v74
	v_mul_f32_e32 v75, v77, v77
	v_fmac_f32_e32 v75, v81, v81
	v_add_f32_e32 v78, v75, v74
	v_pk_add_f32 v[74:75], v[66:67], v[98:99]
	v_pk_add_f32 v[76:77], v[68:69], v[100:101]
	v_mul_f32_e32 v66, v74, v74
	v_fmac_f32_e32 v66, v70, v70
	v_mul_f32_e32 v67, v75, v75
	v_add_f32_e32 v66, v66, v78
	v_fmac_f32_e32 v67, v71, v71
	v_pk_add_f32 v[72:73], v[72:73], v[104:105]
	v_add_f32_e32 v66, v67, v66
	v_mul_f32_e32 v67, v76, v76
	v_fmac_f32_e32 v67, v72, v72
	v_add_f32_e32 v66, v67, v66
	v_mul_f32_e32 v67, v77, v77
	v_fmac_f32_e32 v67, v73, v73
	v_add_f32_e32 v66, v67, v66
	ds_bpermute_b32 v67, v169, v66
	v_lshlrev_b64 v[110:111], 11, v[130:131]
	v_lshl_add_u64 v[110:111], s[2:3], 0, v[110:111]
	v_lshl_add_u64 v[110:111], v[156:157], 1, v[110:111]
	global_store_dwordx4 v[110:111], v[106:109], off nt
	global_store_dwordx4 v[132:133], v[70:73], off offset:512 nt
	global_store_dwordx4 v[132:133], v[74:77], off offset:528 nt
	s_waitcnt lgkmcnt(0)
	v_add_f32_e32 v66, v66, v67
	ds_bpermute_b32 v67, v170, v66
	v_cvt_pk_bf16_f32 v68, v70, v71
	v_cvt_pk_bf16_f32 v69, v72, v73
	v_cvt_pk_bf16_f32 v70, v74, v75
	v_cvt_pk_bf16_f32 v71, v76, v77
	global_store_dwordx4 v[110:111], v[68:71], off offset:256 nt
	s_and_saveexec_b64 s[16:17], vcc
	s_cbranch_execz .LBB0_859
	v_lshl_add_u64 v[68:69], v[130:131], 2, s[8:9]
	s_waitcnt lgkmcnt(0)
	v_add_f32_e32 v66, v66, v67
	global_atomic_add_f32 v[68:69], v66, off
; #define NTL(p) __builtin_nontemporal_load((const f32x4*)(p))
; #define NTS(v, p) __builtin_nontemporal_store((v), (f32x4*)(p))
; __device__ __forceinline__ unsigned cvt_pk_bf16(float lo, float hi) { unsigned r; asm volatile("v_cvt_pk_bf16_f32 %0, %1, %2" : "=v"(r) : "v"(lo), "v"(hi)); return r; }
;     __device__ __forceinline__ void operator()(AccT& acc, const Unit& u, int wr, int wc, int fr, int fq) const {
;     ...
;         for (int r = 0; r < 8; ++r) { const int ai = r >> 2, m = r & 3; const int row = row0 + ai * 128 + m * 16;
;             if (r < 7) { const int rn = row0 + ((r + 1) >> 2) * 128 + ((r + 1) & 3) * 16; const float* hn = H + (size_t)rn * DM + col0;
;                 hv[(r + 1) & 1][0] = NTL(hn); hv[(r + 1) & 1][1] = NTL(hn + 4); hv[(r + 1) & 1][2] = NTL(hn + 128); hv[(r + 1) & 1][3] = NTL(hn + 132); }
;             float* hr = H + (size_t)row * DM + col0; float ss = 0.f;
; #pragma unroll
;             for (int bj = 0; bj < 2; ++bj) {
;                 f32x4 v0 = acc[ai][bj][m][0] + hv[r & 1][2 * bj], v1 = acc[ai][bj][m][1] + hv[r & 1][2 * bj + 1];
;                 NTS(v0, hr + bj * 128); NTS(v1, hr + bj * 128 + 4);
;                 u32x4 w; w.x = cvt_pk_bf16(v0[0], v0[1]); w.y = cvt_pk_bf16(v0[2], v0[3]); w.z = cvt_pk_bf16(v1[0], v1[1]); w.w = cvt_pk_bf16(v1[2], v1[3]);
;                 *(u32x4*)(HB + (size_t)row * DM + col0 + bj * 128) = w;
; #pragma unroll
;                 for (int j = 0; j < 4; ++j) ss += v0[j] * v0[j] + v1[j] * v1[j]; }
;             ss += __shfl_xor(ss, 16); ss += __shfl_xor(ss, 32);
;             if (fq == 0) unsafeAtomicAdd(rss + row, ss); __builtin_amdgcn_sched_barrier(0); }
.LBB0_859:
	s_or_b64 exec, exec, s[16:17]
	v_add_u32_e32 v98, 0x90, v158
	v_ashrrev_i32_e32 v99, 31, v98
	s_waitcnt lgkmcnt(0)
	v_lshlrev_b64 v[66:67], 12, v[98:99]
	v_lshl_add_u64 v[66:67], s[22:23], 0, v[66:67]
	v_lshl_add_u64 v[100:101], v[156:157], 2, v[66:67]
	global_load_dwordx4 v[74:77], v[100:101], off offset:16 nt
	global_load_dwordx4 v[78:81], v[100:101], off nt
	global_load_dwordx4 v[66:69], v[100:101], off offset:528 nt
	global_load_dwordx4 v[70:73], v[100:101], off offset:512 nt
	s_waitcnt vmcnt(12)
	v_pk_add_f32 v[64:65], v[64:65], v[96:97]
	v_pk_add_f32 v[62:63], v[62:63], v[94:95]
	v_pk_add_f32 v[58:59], v[58:59], v[90:91]
	v_pk_add_f32 v[60:61], v[60:61], v[92:93]
	global_store_dwordx4 v[116:117], v[62:65], off nt
	global_store_dwordx4 v[116:117], v[58:61], off offset:16 nt
	v_cvt_pk_bf16_f32 v90, v62, v63
	v_cvt_pk_bf16_f32 v91, v64, v65
	v_cvt_pk_bf16_f32 v92, v58, v59
	s_waitcnt vmcnt(12)
	v_pk_add_f32 v[54:55], v[54:55], v[86:87]
	v_cvt_pk_bf16_f32 v93, v60, v61
	v_mul_f32_e32 v58, v58, v58
	v_mul_f32_e32 v59, v59, v59
	v_fmac_f32_e32 v58, v62, v62
	v_fmac_f32_e32 v59, v63, v63
	v_add_f32_e32 v58, v58, v59
	v_mul_f32_e32 v59, v60, v60
	v_fmac_f32_e32 v59, v64, v64
	v_add_f32_e32 v58, v59, v58
	v_mul_f32_e32 v59, v61, v61
	v_fmac_f32_e32 v59, v65, v65
	v_add_f32_e32 v62, v59, v58
	v_pk_add_f32 v[58:59], v[50:51], v[82:83]
	v_pk_add_f32 v[60:61], v[52:53], v[84:85]
	v_mul_f32_e32 v50, v58, v58
	v_fmac_f32_e32 v50, v54, v54
	v_mul_f32_e32 v51, v59, v59
	v_add_f32_e32 v50, v50, v62
	v_fmac_f32_e32 v51, v55, v55
	v_pk_add_f32 v[56:57], v[56:57], v[88:89]
	v_add_f32_e32 v50, v51, v50
	v_mul_f32_e32 v51, v60, v60
	v_fmac_f32_e32 v51, v56, v56
	v_add_f32_e32 v50, v51, v50
	v_mul_f32_e32 v51, v61, v61
	v_fmac_f32_e32 v51, v57, v57
	v_add_f32_e32 v50, v51, v50
	ds_bpermute_b32 v51, v169, v50
	v_lshlrev_b64 v[94:95], 11, v[114:115]
	v_lshl_add_u64 v[94:95], s[2:3], 0, v[94:95]
	v_lshl_add_u64 v[94:95], v[156:157], 1, v[94:95]
	global_store_dwordx4 v[94:95], v[90:93], off nt
	global_store_dwordx4 v[116:117], v[54:57], off offset:512 nt
	global_store_dwordx4 v[116:117], v[58:61], off offset:528 nt
	s_waitcnt lgkmcnt(0)
	v_add_f32_e32 v50, v50, v51
	ds_bpermute_b32 v51, v170, v50
	v_cvt_pk_bf16_f32 v52, v54, v55
	v_cvt_pk_bf16_f32 v53, v56, v57
	v_cvt_pk_bf16_f32 v54, v58, v59
	v_cvt_pk_bf16_f32 v55, v60, v61
	global_store_dwordx4 v[94:95], v[52:55], off offset:256 nt
	s_and_saveexec_b64 s[16:17], vcc
	s_cbranch_execz .LBB0_861
	v_lshl_add_u64 v[52:53], v[114:115], 2, s[8:9]
	s_waitcnt lgkmcnt(0)
	v_add_f32_e32 v50, v50, v51
	global_atomic_add_f32 v[52:53], v50, off
.LBB0_861:
	s_or_b64 exec, exec, s[16:17]
	v_add_u32_e32 v82, 0xa0, v158
	v_ashrrev_i32_e32 v83, 31, v82
	s_waitcnt lgkmcnt(0)
	v_lshlrev_b64 v[50:51], 12, v[82:83]
	v_lshl_add_u64 v[50:51], s[22:23], 0, v[50:51]
	v_lshl_add_u64 v[84:85], v[156:157], 2, v[50:51]
	global_load_dwordx4 v[58:61], v[84:85], off offset:16 nt
	global_load_dwordx4 v[62:65], v[84:85], off nt
	global_load_dwordx4 v[50:53], v[84:85], off offset:528 nt
	global_load_dwordx4 v[54:57], v[84:85], off offset:512 nt
	s_waitcnt vmcnt(12)
	v_pk_add_f32 v[48:49], v[48:49], v[80:81]
	v_pk_add_f32 v[46:47], v[46:47], v[78:79]
	v_pk_add_f32 v[42:43], v[42:43], v[74:75]
	v_pk_add_f32 v[44:45], v[44:45], v[76:77]
	global_store_dwordx4 v[100:101], v[46:49], off nt
	global_store_dwordx4 v[100:101], v[42:45], off offset:16 nt
	v_cvt_pk_bf16_f32 v74, v46, v47
	v_cvt_pk_bf16_f32 v75, v48, v49
	v_cvt_pk_bf16_f32 v76, v42, v43
	s_waitcnt vmcnt(12)
	v_pk_add_f32 v[38:39], v[38:39], v[70:71]
	v_cvt_pk_bf16_f32 v77, v44, v45
	v_mul_f32_e32 v42, v42, v42
	v_mul_f32_e32 v43, v43, v43
	v_fmac_f32_e32 v42, v46, v46
	v_fmac_f32_e32 v43, v47, v47
	v_add_f32_e32 v42, v42, v43
	v_mul_f32_e32 v43, v44, v44
	v_fmac_f32_e32 v43, v48, v48
	v_add_f32_e32 v42, v43, v42
	v_mul_f32_e32 v43, v45, v45
	v_fmac_f32_e32 v43, v49, v49
	v_add_f32_e32 v46, v43, v42
	v_pk_add_f32 v[42:43], v[34:35], v[66:67]
	v_pk_add_f32 v[44:45], v[36:37], v[68:69]
	v_mul_f32_e32 v34, v42, v42
	v_fmac_f32_e32 v34, v38, v38
	v_mul_f32_e32 v35, v43, v43
	v_add_f32_e32 v34, v34, v46
	v_fmac_f32_e32 v35, v39, v39
	v_pk_add_f32 v[40:41], v[40:41], v[72:73]
	v_add_f32_e32 v34, v35, v34
	v_mul_f32_e32 v35, v44, v44
	v_fmac_f32_e32 v35, v40, v40
	v_add_f32_e32 v34, v35, v34
	v_mul_f32_e32 v35, v45, v45
	v_fmac_f32_e32 v35, v41, v41
	v_add_f32_e32 v34, v35, v34
	ds_bpermute_b32 v35, v169, v34
	v_lshlrev_b64 v[78:79], 11, v[98:99]
	v_lshl_add_u64 v[78:79], s[2:3], 0, v[78:79]
	v_lshl_add_u64 v[78:79], v[156:157], 1, v[78:79]
	global_store_dwordx4 v[78:79], v[74:77], off nt
	global_store_dwordx4 v[100:101], v[38:41], off offset:512 nt
	global_store_dwordx4 v[100:101], v[42:45], off offset:528 nt
	s_waitcnt lgkmcnt(0)
	v_add_f32_e32 v34, v34, v35
	ds_bpermute_b32 v35, v170, v34
	v_cvt_pk_bf16_f32 v36, v38, v39
	v_cvt_pk_bf16_f32 v37, v40, v41
	v_cvt_pk_bf16_f32 v38, v42, v43
	v_cvt_pk_bf16_f32 v39, v44, v45
	global_store_dwordx4 v[78:79], v[36:39], off offset:256 nt
	s_and_saveexec_b64 s[16:17], vcc
	s_cbranch_execz .LBB0_863
	v_lshl_add_u64 v[36:37], v[98:99], 2, s[8:9]
	s_waitcnt lgkmcnt(0)
	v_add_f32_e32 v34, v34, v35
	global_atomic_add_f32 v[36:37], v34, off
; #define NTL(p) __builtin_nontemporal_load((const f32x4*)(p))
; #define NTS(v, p) __builtin_nontemporal_store((v), (f32x4*)(p))
; __device__ __forceinline__ unsigned cvt_pk_bf16(float lo, float hi) { unsigned r; asm volatile("v_cvt_pk_bf16_f32 %0, %1, %2" : "=v"(r) : "v"(lo), "v"(hi)); return r; }
;     __device__ __forceinline__ void operator()(AccT& acc, const Unit& u, int wr, int wc, int fr, int fq) const {
;     ...
;         for (int r = 0; r < 8; ++r) { const int ai = r >> 2, m = r & 3; const int row = row0 + ai * 128 + m * 16;
;             if (r < 7) { const int rn = row0 + ((r + 1) >> 2) * 128 + ((r + 1) & 3) * 16; const float* hn = H + (size_t)rn * DM + col0;
;                 hv[(r + 1) & 1][0] = NTL(hn); hv[(r + 1) & 1][1] = NTL(hn + 4); hv[(r + 1) & 1][2] = NTL(hn + 128); hv[(r + 1) & 1][3] = NTL(hn + 132); }
;             float* hr = H + (size_t)row * DM + col0; float ss = 0.f;
; #pragma unroll
;             for (int bj = 0; bj < 2; ++bj) {
;                 f32x4 v0 = acc[ai][bj][m][0] + hv[r & 1][2 * bj], v1 = acc[ai][bj][m][1] + hv[r & 1][2 * bj + 1];
;                 NTS(v0, hr + bj * 128); NTS(v1, hr + bj * 128 + 4);
;                 u32x4 w; w.x = cvt_pk_bf16(v0[0], v0[1]); w.y = cvt_pk_bf16(v0[2], v0[3]); w.z = cvt_pk_bf16(v1[0], v1[1]); w.w = cvt_pk_bf16(v1[2], v1[3]);
;                 *(u32x4*)(HB + (size_t)row * DM + col0 + bj * 128) = w;
; #pragma unroll
;                 for (int j = 0; j < 4; ++j) ss += v0[j] * v0[j] + v1[j] * v1[j]; }
;             ss += __shfl_xor(ss, 16); ss += __shfl_xor(ss, 32);
;             if (fq == 0) unsafeAtomicAdd(rss + row, ss); __builtin_amdgcn_sched_barrier(0); }
.LBB0_863:
	s_or_b64 exec, exec, s[16:17]
	v_add_u32_e32 v66, 0xb0, v158
	v_ashrrev_i32_e32 v67, 31, v66
	s_waitcnt lgkmcnt(0)
	v_lshlrev_b64 v[34:35], 12, v[66:67]
	v_lshl_add_u64 v[34:35], s[22:23], 0, v[34:35]
	v_lshl_add_u64 v[68:69], v[156:157], 2, v[34:35]
	global_load_dwordx4 v[42:45], v[68:69], off offset:16 nt
	global_load_dwordx4 v[46:49], v[68:69], off nt
	global_load_dwordx4 v[34:37], v[68:69], off offset:528 nt
	global_load_dwordx4 v[38:41], v[68:69], off offset:512 nt
	s_waitcnt vmcnt(12)
	v_pk_add_f32 v[32:33], v[32:33], v[64:65]
	v_pk_add_f32 v[30:31], v[30:31], v[62:63]
	v_pk_add_f32 v[26:27], v[26:27], v[58:59]
	v_pk_add_f32 v[28:29], v[28:29], v[60:61]
	global_store_dwordx4 v[84:85], v[30:33], off nt
	global_store_dwordx4 v[84:85], v[26:29], off offset:16 nt
	v_cvt_pk_bf16_f32 v58, v30, v31
	v_cvt_pk_bf16_f32 v59, v32, v33
	v_cvt_pk_bf16_f32 v60, v26, v27
	s_waitcnt vmcnt(12)
	v_pk_add_f32 v[22:23], v[22:23], v[54:55]
	v_cvt_pk_bf16_f32 v61, v28, v29
	v_mul_f32_e32 v26, v26, v26
	v_mul_f32_e32 v27, v27, v27
	v_fmac_f32_e32 v26, v30, v30
	v_fmac_f32_e32 v27, v31, v31
	v_add_f32_e32 v26, v26, v27
	v_mul_f32_e32 v27, v28, v28
	v_fmac_f32_e32 v27, v32, v32
	v_add_f32_e32 v26, v27, v26
	v_mul_f32_e32 v27, v29, v29
	v_fmac_f32_e32 v27, v33, v33
	v_add_f32_e32 v30, v27, v26
	v_pk_add_f32 v[26:27], v[18:19], v[50:51]
	v_pk_add_f32 v[28:29], v[20:21], v[52:53]
	v_mul_f32_e32 v18, v26, v26
	v_fmac_f32_e32 v18, v22, v22
	v_mul_f32_e32 v19, v27, v27
	v_add_f32_e32 v18, v18, v30
	v_fmac_f32_e32 v19, v23, v23
	v_pk_add_f32 v[24:25], v[24:25], v[56:57]
	v_add_f32_e32 v18, v19, v18
	v_mul_f32_e32 v19, v28, v28
	v_fmac_f32_e32 v19, v24, v24
	v_add_f32_e32 v18, v19, v18
	v_mul_f32_e32 v19, v29, v29
	v_fmac_f32_e32 v19, v25, v25
	v_add_f32_e32 v18, v19, v18
	ds_bpermute_b32 v19, v169, v18
	v_lshlrev_b64 v[62:63], 11, v[82:83]
	v_lshl_add_u64 v[62:63], s[2:3], 0, v[62:63]
	v_lshl_add_u64 v[62:63], v[156:157], 1, v[62:63]
	global_store_dwordx4 v[62:63], v[58:61], off nt
	global_store_dwordx4 v[84:85], v[22:25], off offset:512 nt
	global_store_dwordx4 v[84:85], v[26:29], off offset:528 nt
	s_waitcnt lgkmcnt(0)
	v_add_f32_e32 v18, v18, v19
	ds_bpermute_b32 v19, v170, v18
	v_cvt_pk_bf16_f32 v20, v22, v23
	v_cvt_pk_bf16_f32 v21, v24, v25
	v_cvt_pk_bf16_f32 v22, v26, v27
	v_cvt_pk_bf16_f32 v23, v28, v29
	global_store_dwordx4 v[62:63], v[20:23], off offset:256 nt
	s_and_saveexec_b64 s[16:17], vcc
	s_cbranch_execz .LBB0_865
	v_lshl_add_u64 v[20:21], v[82:83], 2, s[8:9]
	s_waitcnt lgkmcnt(0)
	v_add_f32_e32 v18, v18, v19
	global_atomic_add_f32 v[20:21], v18, off
.LBB0_865:
	s_or_b64 exec, exec, s[16:17]
	s_waitcnt vmcnt(8)
	v_pk_add_f32 v[16:17], v[16:17], v[48:49]
	v_pk_add_f32 v[14:15], v[14:15], v[46:47]
	v_pk_add_f32 v[10:11], v[10:11], v[42:43]
	v_pk_add_f32 v[12:13], v[12:13], v[44:45]
	global_store_dwordx4 v[68:69], v[14:17], off nt
	global_store_dwordx4 v[68:69], v[10:13], off offset:16 nt
	v_cvt_pk_bf16_f32 v18, v14, v15
	s_waitcnt lgkmcnt(0)
	v_cvt_pk_bf16_f32 v19, v16, v17
	v_cvt_pk_bf16_f32 v20, v10, v11
	s_waitcnt vmcnt(8)
	v_pk_add_f32 v[6:7], v[6:7], v[38:39]
	v_cvt_pk_bf16_f32 v21, v12, v13
	v_mul_f32_e32 v10, v10, v10
	v_mul_f32_e32 v11, v11, v11
	v_fmac_f32_e32 v10, v14, v14
	v_fmac_f32_e32 v11, v15, v15
	v_add_f32_e32 v10, v10, v11
	v_mul_f32_e32 v11, v12, v12
	v_fmac_f32_e32 v11, v16, v16
	v_add_f32_e32 v10, v11, v10
	v_mul_f32_e32 v11, v13, v13
	v_fmac_f32_e32 v11, v17, v17
	v_add_f32_e32 v14, v11, v10
	v_pk_add_f32 v[10:11], v[2:3], v[34:35]
	v_pk_add_f32 v[12:13], v[4:5], v[36:37]
	v_mul_f32_e32 v2, v10, v10
	v_fmac_f32_e32 v2, v6, v6
	v_mul_f32_e32 v3, v11, v11
	v_add_f32_e32 v2, v2, v14
	v_fmac_f32_e32 v3, v7, v7
	v_pk_add_f32 v[8:9], v[8:9], v[40:41]
	v_add_f32_e32 v2, v3, v2
	v_mul_f32_e32 v3, v12, v12
	v_fmac_f32_e32 v3, v8, v8
	v_add_f32_e32 v2, v3, v2
	v_mul_f32_e32 v3, v13, v13
	v_fmac_f32_e32 v3, v9, v9
	v_add_f32_e32 v2, v3, v2
	ds_bpermute_b32 v3, v169, v2
	v_lshlrev_b64 v[22:23], 11, v[66:67]
	v_lshl_add_u64 v[22:23], s[2:3], 0, v[22:23]
	v_lshl_add_u64 v[22:23], v[156:157], 1, v[22:23]
	global_store_dwordx4 v[22:23], v[18:21], off nt
	global_store_dwordx4 v[68:69], v[6:9], off offset:512 nt
	global_store_dwordx4 v[68:69], v[10:13], off offset:528 nt
	s_waitcnt lgkmcnt(0)
	v_add_f32_e32 v2, v2, v3
	ds_bpermute_b32 v3, v170, v2
	v_cvt_pk_bf16_f32 v4, v6, v7
	v_cvt_pk_bf16_f32 v5, v8, v9
	v_cvt_pk_bf16_f32 v6, v10, v11
	v_cvt_pk_bf16_f32 v7, v12, v13
	global_store_dwordx4 v[22:23], v[4:7], off offset:256 nt
	s_and_saveexec_b64 s[16:17], vcc
	s_cbranch_execz .LBB0_836
	v_lshl_add_u64 v[4:5], v[66:67], 2, s[8:9]
	s_waitcnt lgkmcnt(0)
	v_add_f32_e32 v2, v2, v3
	global_atomic_add_f32 v[4:5], v2, off
	s_branch .LBB0_836
